# attention loops: fragment ds_reads feeding non-BAR P.V blocks hoisted to the start of the preceding W block (above ds_writes/global loads), lgkmcnt ladder re-derived
# speedup vs baseline: 1.0032x; 1.0032x over previous
.LBB0_641:
	s_add_i32 s24, s23, -7
	s_lshl_b32 s92, s24, 13
	s_add_u32 vcc_lo, s100, s92
	s_addc_u32 vcc_hi, s101, 0
	global_load_dwordx4 v[52:55], v248, vcc
	s_add_i32 s24, s23, -8
	s_lshl_b32 s92, s24, 7
	s_add_u32 vcc_lo, s98, s92
	s_addc_u32 vcc_hi, s99, 0
	global_load_dwordx4 v[56:59], v249, vcc
	s_mul_i32 s26, s25, 0x2400
	s_add_i32 s24, s23, -7
	s_add_i32 s27, s26, 0xffffdc00
	s_cmp_lg_u32 s25, 0
	s_cselect_b32 s27, s27, 0x9000
	v_add_u32_e32 v1, s27, v163
	ds_read_b128 v[60:63], v1 offset:36864
	ds_read_b128 v[114:117], v1 offset:36896
	ds_read_b128 v[118:121], v1 offset:41472
	ds_read_b128 v[134:137], v1 offset:41504
	ds_read_b128 v[146:149], v1 offset:36928
	ds_read_b128 v[150:153], v1 offset:36960
	ds_read_b128 v[196:199], v1 offset:41536
	ds_read_b128 v[200:203], v1 offset:41568
	s_setprio 3
	v_cvt_pk_bf16_f32 v204, v102, v103
	v_cvt_pk_bf16_f32 v205, v104, v105
	v_cvt_pk_bf16_f32 v206, v98, v99
	v_cvt_pk_bf16_f32 v207, v100, v101
	s_waitcnt lgkmcnt(7)
	s_nop 0
	v_mfma_f32_32x32x16_bf16 v[18:33], v[60:63], v[204:207], v[18:33]
	v_add_f32_e32 v1, v102, v103
	v_add_f32_e32 v1, v1, v104
	v_add_f32_e32 v1, v1, v105
	s_waitcnt lgkmcnt(5)
	v_mfma_f32_32x32x16_bf16 v[2:17], v[118:121], v[204:207], v[2:17]
	v_cvt_pk_bf16_f32 v60, v194, v187
	v_cvt_pk_bf16_f32 v61, v186, v185
	v_cvt_pk_bf16_f32 v62, v133, v132
	v_cvt_pk_bf16_f32 v63, v131, v130
	v_add_f32_e32 v1, v1, v98
	v_add_f32_e32 v1, v1, v99
	v_add_f32_e32 v1, v1, v100
	v_add_f32_e32 v1, v1, v101
	s_nop 0
	v_mfma_f32_32x32x16_bf16 v[18:33], v[114:117], v[60:63], v[18:33]
	v_add_f32_e32 v1, v1, v194
	v_add_f32_e32 v1, v1, v187
	v_add_f32_e32 v1, v1, v186
	v_add_f32_e32 v1, v1, v185
	s_waitcnt lgkmcnt(4)
	v_mfma_f32_32x32x16_bf16 v[2:17], v[134:137], v[60:63], v[2:17]
	v_cvt_pk_bf16_f32 v98, v129, v128
	v_cvt_pk_bf16_f32 v99, v127, v126
	v_cvt_pk_bf16_f32 v100, v125, v124
	v_cvt_pk_bf16_f32 v101, v123, v122
	v_add_f32_e32 v1, v1, v133
	v_add_f32_e32 v1, v1, v132
	v_add_f32_e32 v1, v1, v131
	v_add_f32_e32 v1, v1, v130
	s_waitcnt lgkmcnt(3)
	v_mfma_f32_32x32x16_bf16 v[18:33], v[146:149], v[98:101], v[18:33]
	v_add_f32_e32 v1, v1, v129
	v_add_f32_e32 v1, v1, v128
	v_add_f32_e32 v1, v1, v127
	v_add_f32_e32 v1, v1, v126
	s_waitcnt lgkmcnt(1)
	v_mfma_f32_32x32x16_bf16 v[2:17], v[196:199], v[98:101], v[2:17]
	v_cvt_pk_bf16_f32 v60, v109, v108
	v_cvt_pk_bf16_f32 v61, v107, v106
	v_cvt_pk_bf16_f32 v62, v113, v112
	v_cvt_pk_bf16_f32 v63, v111, v110
	v_add_f32_e32 v1, v1, v125
	v_add_f32_e32 v1, v1, v124
	v_add_f32_e32 v1, v1, v123
	v_add_f32_e32 v1, v1, v122
	s_nop 0
	v_mfma_f32_32x32x16_bf16 v[18:33], v[150:153], v[60:63], v[18:33]
	v_add_f32_e32 v1, v1, v109
	v_add_f32_e32 v1, v1, v108
	v_add_f32_e32 v1, v1, v107
	v_add_f32_e32 v1, v1, v106
	s_waitcnt lgkmcnt(0)
	v_mfma_f32_32x32x16_bf16 v[2:17], v[200:203], v[60:63], v[2:17]
	v_add_f32_e32 v1, v1, v113
	v_add_f32_e32 v1, v1, v112
	v_add_f32_e32 v1, v1, v111
	v_add_f32_e32 v1, v1, v110
	s_setprio 2
	s_waitcnt lgkmcnt(0)
	s_barrier
	ds_read_b128 v[240:243], v165 offset:18432
	ds_read_b128 v[244:247], v165 offset:23040
	ds_read_b128 v[130:133], v165 offset:18464
	ds_read_b128 v[146:149], v165 offset:23072
	s_waitcnt lgkmcnt(2)
	v_mfma_f32_32x32x16_bf16 v[114:129], v[240:243], v[158:161], v[34:49]
	v_exp_f32_e32 v185, v82
	v_exp_f32_e32 v186, v83
	v_exp_f32_e32 v187, v84
	v_exp_f32_e32 v194, v85
	v_exp_f32_e32 v195, v86
	v_exp_f32_e32 v196, v87
	v_exp_f32_e32 v197, v88
	v_exp_f32_e32 v198, v89
	s_waitcnt lgkmcnt(1)
	v_mfma_f32_32x32x16_bf16 v[98:113], v[244:247], v[158:161], v[34:49]
	v_exp_f32_e32 v199, v90
	v_exp_f32_e32 v200, v91
	v_exp_f32_e32 v201, v92
	v_exp_f32_e32 v202, v93
	v_exp_f32_e32 v134, v94
	v_exp_f32_e32 v135, v95
	v_exp_f32_e32 v136, v96
	v_exp_f32_e32 v137, v97
	v_mfma_f32_32x32x16_bf16 v[114:129], v[130:133], v[154:157], v[114:129]
	v_exp_f32_e32 v96, v66
	v_exp_f32_e32 v97, v67
	v_exp_f32_e32 v203, v68
	v_exp_f32_e32 v204, v69
	v_exp_f32_e32 v130, v70
	v_exp_f32_e32 v131, v71
	v_exp_f32_e32 v132, v72
	v_exp_f32_e32 v133, v73
	s_waitcnt lgkmcnt(0)
	v_mfma_f32_32x32x16_bf16 v[98:113], v[146:149], v[154:157], v[98:113]
	v_exp_f32_e32 v205, v74
	v_exp_f32_e32 v206, v75
	v_exp_f32_e32 v207, v76
	v_exp_f32_e32 v208, v77
	v_exp_f32_e32 v209, v78
	v_exp_f32_e32 v210, v79
	v_exp_f32_e32 v211, v80
	v_exp_f32_e32 v212, v81
	v_add_u32_e32 v88, s26, v163
	ds_read_b128 v[240:243], v165 offset:27648
	ds_read_b128 v[244:247], v165 offset:32256
	ds_read_b128 v[60:63], v88 offset:41472
	ds_read_b128 v[64:67], v88 offset:36864
	ds_read_b128 v[68:71], v88 offset:36896
	ds_read_b128 v[72:75], v88 offset:41504
	ds_read_b128 v[76:79], v88 offset:36928
	ds_read_b128 v[80:83], v88 offset:41536
	ds_read_b128 v[84:87], v88 offset:36960
	ds_read_b128 v[88:91], v88 offset:41568
	s_cmp_gt_i32 s25, 2
	s_cselect_b32 s27, -3, 2
	s_add_i32 s27, s27, s25
	s_add_i32 s26, s23, -6
	s_mulk_i32 s27, 0x2400
	s_min_u32 s26, s26, s13
	v_add_u32_e32 v51, s27, v182
	s_min_u32 s24, s24, s13
	s_lshl_b32 s92, s26, 13
	s_waitcnt vmcnt(3)
	ds_write_b128 v182, v[138:141]
	s_waitcnt vmcnt(2)
	ds_write_b128 v51, v[142:145] offset:36864
	v_add_f32_e32 v1, v50, v1
	s_add_u32 vcc_lo, s100, s92
	s_addc_u32 vcc_hi, s101, 0
	global_load_dwordx4 v[146:149], v248, vcc
	s_lshl_b32 s92, s24, 7
	s_add_u32 vcc_lo, s98, s92
	s_addc_u32 vcc_hi, s99, 0
	global_load_dwordx4 v[150:153], v249, vcc
	s_add_i32 s27, s25, 1
	s_setprio 1
	v_cvt_pk_bf16_f32 v92, v185, v186
	v_cvt_pk_bf16_f32 v93, v187, v194
	v_cvt_pk_bf16_f32 v94, v195, v196
	v_cvt_pk_bf16_f32 v95, v197, v198
	s_waitcnt lgkmcnt(8)
	s_nop 0
	v_mfma_f32_32x32x16_bf16 v[18:33], v[64:67], v[92:95], v[18:33]
	v_add_f32_e32 v213, v185, v186
	v_add_f32_e32 v213, v213, v187
	v_add_f32_e32 v213, v213, v194
	s_nop 0
	v_mfma_f32_32x32x16_bf16 v[2:17], v[60:63], v[92:95], v[2:17]
	v_cvt_pk_bf16_f32 v64, v199, v200
	v_cvt_pk_bf16_f32 v65, v201, v202
	v_cvt_pk_bf16_f32 v66, v134, v135
	v_cvt_pk_bf16_f32 v67, v136, v137
	v_add_f32_e32 v213, v213, v195
	v_add_f32_e32 v213, v213, v196
	v_add_f32_e32 v213, v213, v197
	v_add_f32_e32 v213, v213, v198
	s_waitcnt lgkmcnt(7)
	v_mfma_f32_32x32x16_bf16 v[18:33], v[68:71], v[64:67], v[18:33]
	v_add_f32_e32 v213, v213, v199
	v_add_f32_e32 v213, v213, v200
	v_add_f32_e32 v213, v213, v201
	v_add_f32_e32 v213, v213, v202
	s_waitcnt lgkmcnt(6)
	v_mfma_f32_32x32x16_bf16 v[2:17], v[72:75], v[64:67], v[2:17]
	v_cvt_pk_bf16_f32 v60, v96, v97
	v_cvt_pk_bf16_f32 v61, v203, v204
	v_cvt_pk_bf16_f32 v62, v130, v131
	v_cvt_pk_bf16_f32 v63, v132, v133
	v_add_f32_e32 v213, v213, v134
	v_add_f32_e32 v213, v213, v135
	v_add_f32_e32 v213, v213, v136
	v_add_f32_e32 v213, v213, v137
	s_waitcnt lgkmcnt(5)
	v_mfma_f32_32x32x16_bf16 v[18:33], v[76:79], v[60:63], v[18:33]
	v_add_f32_e32 v213, v213, v96
	v_add_f32_e32 v213, v213, v97
	v_add_f32_e32 v213, v213, v203
	v_add_f32_e32 v213, v213, v204
	s_waitcnt lgkmcnt(4)
	v_mfma_f32_32x32x16_bf16 v[2:17], v[80:83], v[60:63], v[2:17]
	v_cvt_pk_bf16_f32 v64, v205, v206
	v_cvt_pk_bf16_f32 v65, v207, v208
	v_cvt_pk_bf16_f32 v66, v209, v210
	v_cvt_pk_bf16_f32 v67, v211, v212
	v_add_f32_e32 v213, v213, v130
	v_add_f32_e32 v213, v213, v131
	v_add_f32_e32 v213, v213, v132
	v_add_f32_e32 v213, v213, v133
	s_waitcnt lgkmcnt(3)
	v_mfma_f32_32x32x16_bf16 v[18:33], v[84:87], v[64:67], v[18:33]
	v_add_f32_e32 v213, v213, v205
	v_add_f32_e32 v213, v213, v206
	v_add_f32_e32 v213, v213, v207
	v_add_f32_e32 v213, v213, v208
	s_waitcnt lgkmcnt(2)
	v_mfma_f32_32x32x16_bf16 v[2:17], v[88:91], v[64:67], v[2:17]
	v_add_f32_e32 v213, v213, v209
	v_add_f32_e32 v213, v213, v210
	v_add_f32_e32 v213, v213, v211
	v_add_f32_e32 v213, v213, v212
	s_setprio 0
	ds_read_b128 v[64:67], v165 offset:27680
	ds_read_b128 v[72:75], v165 offset:32288
	s_cmp_lg_u32 s25, 4
	s_cselect_b32 s24, s27, 0
	s_waitcnt lgkmcnt(2)
	v_mfma_f32_32x32x16_bf16 v[130:145], v[240:243], v[158:161], v[34:49]
	v_exp_f32_e32 v185, v114
	v_exp_f32_e32 v186, v115
	v_exp_f32_e32 v187, v116
	v_exp_f32_e32 v194, v117
	v_exp_f32_e32 v195, v118
	v_exp_f32_e32 v196, v119
	v_exp_f32_e32 v197, v120
	v_exp_f32_e32 v198, v121
	s_waitcnt lgkmcnt(1)
	v_mfma_f32_32x32x16_bf16 v[82:97], v[244:247], v[158:161], v[34:49]
	v_exp_f32_e32 v199, v122
	v_exp_f32_e32 v200, v123
	v_exp_f32_e32 v201, v124
	v_exp_f32_e32 v202, v125
	v_exp_f32_e32 v122, v126
	v_exp_f32_e32 v123, v127
	v_exp_f32_e32 v124, v128
	v_exp_f32_e32 v125, v129
	v_mfma_f32_32x32x16_bf16 v[130:145], v[64:67], v[154:157], v[130:145]
	v_exp_f32_e32 v126, v98
	v_exp_f32_e32 v127, v99
	v_exp_f32_e32 v128, v100
	v_exp_f32_e32 v129, v101
	v_exp_f32_e32 v203, v102
	v_exp_f32_e32 v204, v103
	v_exp_f32_e32 v205, v104
	v_exp_f32_e32 v206, v105
	s_waitcnt lgkmcnt(0)
	v_mfma_f32_32x32x16_bf16 v[82:97], v[72:75], v[154:157], v[82:97]
	v_exp_f32_e32 v102, v106
	v_exp_f32_e32 v103, v107
	v_exp_f32_e32 v104, v108
	v_exp_f32_e32 v105, v109
	v_exp_f32_e32 v106, v110
	v_exp_f32_e32 v107, v111
	v_exp_f32_e32 v108, v112
	v_exp_f32_e32 v109, v113
	s_cmp_gt_i32 s24, 2
	s_cselect_b32 s25, -3, 2
	s_add_i32 s25, s25, s24
	s_mulk_i32 s25, 0x2400
	v_add_u32_e32 v50, s25, v182
	s_add_i32 s25, s24, 1
	s_cmp_lg_u32 s24, 4
	s_cselect_b32 s24, s25, 0
	s_add_i32 s25, s23, -5
	s_min_u32 s25, s25, s13
	s_lshl_b32 s92, s25, 13
	s_waitcnt vmcnt(3)
	ds_write_b128 v182, v[52:55] offset:9216
	s_waitcnt vmcnt(2)
	ds_write_b128 v50, v[56:59] offset:36864
	s_add_u32 vcc_lo, s100, s92
	s_addc_u32 vcc_hi, s101, 0
	global_load_dwordx4 v[118:121], v248, vcc
	s_lshl_b32 s92, s26, 7
	s_add_u32 vcc_lo, s98, s92
	s_addc_u32 vcc_hi, s99, 0
	global_load_dwordx4 v[114:117], v249, vcc
	s_mul_i32 s26, s24, 0x2400
	s_add_i32 s27, s26, 0xffffdc00
	s_cmp_lg_u32 s24, 0
	s_cselect_b32 s27, s27, 0x9000
	v_add_u32_e32 v78, s27, v163
	ds_read_b128 v[50:53], v78 offset:36864
	ds_read_b128 v[54:57], v78 offset:36896
	ds_read_b128 v[58:61], v78 offset:41472
	ds_read_b128 v[62:65], v78 offset:41504
	ds_read_b128 v[66:69], v78 offset:36928
	ds_read_b128 v[70:73], v78 offset:36960
	ds_read_b128 v[74:77], v78 offset:41536
	ds_read_b128 v[78:81], v78 offset:41568
	s_setprio 3
	v_cvt_pk_bf16_f32 v98, v185, v186
	v_cvt_pk_bf16_f32 v99, v187, v194
	v_cvt_pk_bf16_f32 v100, v195, v196
	v_cvt_pk_bf16_f32 v101, v197, v198
	s_waitcnt lgkmcnt(7)
	s_nop 0
	v_mfma_f32_32x32x16_bf16 v[18:33], v[50:53], v[98:101], v[18:33]
	v_add_f32_e32 v110, v185, v186
	v_add_f32_e32 v110, v110, v187
	v_add_f32_e32 v110, v110, v194
	s_waitcnt lgkmcnt(5)
	v_mfma_f32_32x32x16_bf16 v[2:17], v[58:61], v[98:101], v[2:17]
	v_cvt_pk_bf16_f32 v50, v199, v200
	v_cvt_pk_bf16_f32 v51, v201, v202
	v_cvt_pk_bf16_f32 v52, v122, v123
	v_cvt_pk_bf16_f32 v53, v124, v125
	v_add_f32_e32 v110, v110, v195
	v_add_f32_e32 v110, v110, v196
	v_add_f32_e32 v110, v110, v197
	v_add_f32_e32 v110, v110, v198
	s_nop 0
	v_mfma_f32_32x32x16_bf16 v[18:33], v[54:57], v[50:53], v[18:33]
	v_add_f32_e32 v110, v110, v199
	v_add_f32_e32 v110, v110, v200
	v_add_f32_e32 v110, v110, v201
	v_add_f32_e32 v110, v110, v202
	s_waitcnt lgkmcnt(4)
	v_mfma_f32_32x32x16_bf16 v[2:17], v[62:65], v[50:53], v[2:17]
	v_cvt_pk_bf16_f32 v54, v126, v127
	v_cvt_pk_bf16_f32 v55, v128, v129
	v_cvt_pk_bf16_f32 v56, v203, v204
	v_cvt_pk_bf16_f32 v57, v205, v206
	v_add_f32_e32 v110, v110, v122
	v_add_f32_e32 v110, v110, v123
	v_add_f32_e32 v110, v110, v124
	v_add_f32_e32 v110, v110, v125
	s_waitcnt lgkmcnt(3)
	v_mfma_f32_32x32x16_bf16 v[18:33], v[66:69], v[54:57], v[18:33]
	v_add_f32_e32 v110, v110, v126
	v_add_f32_e32 v110, v110, v127
	v_add_f32_e32 v110, v110, v128
	v_add_f32_e32 v110, v110, v129
	s_waitcnt lgkmcnt(1)
	v_mfma_f32_32x32x16_bf16 v[2:17], v[74:77], v[54:57], v[2:17]
	v_cvt_pk_bf16_f32 v50, v102, v103
	v_cvt_pk_bf16_f32 v51, v104, v105
	v_cvt_pk_bf16_f32 v52, v106, v107
	v_cvt_pk_bf16_f32 v53, v108, v109
	v_add_f32_e32 v110, v110, v203
	v_add_f32_e32 v110, v110, v204
	v_add_f32_e32 v110, v110, v205
	v_add_f32_e32 v110, v110, v206
	s_nop 0
	v_mfma_f32_32x32x16_bf16 v[18:33], v[70:73], v[50:53], v[18:33]
	v_add_f32_e32 v110, v110, v102
	v_add_f32_e32 v110, v110, v103
	v_add_f32_e32 v110, v110, v104
	v_add_f32_e32 v110, v110, v105
	s_waitcnt lgkmcnt(0)
	v_mfma_f32_32x32x16_bf16 v[2:17], v[78:81], v[50:53], v[2:17]
	v_add_f32_e32 v110, v110, v106
	v_add_f32_e32 v110, v110, v107
	v_add_f32_e32 v110, v110, v108
	v_add_f32_e32 v110, v110, v109
	s_setprio 2
	s_waitcnt lgkmcnt(0)
	s_barrier
	ds_read_b128 v[240:243], v165
	ds_read_b128 v[244:247], v165 offset:4608
	ds_read_b128 v[102:105], v165 offset:32
	ds_read_b128 v[106:109], v165 offset:4640
	v_add_f32_e32 v1, v1, v213
	s_waitcnt lgkmcnt(2)
	v_mfma_f32_32x32x16_bf16 v[66:81], v[240:243], v[158:161], v[34:49]
	v_exp_f32_e32 v185, v130
	v_exp_f32_e32 v186, v131
	v_exp_f32_e32 v187, v132
	v_exp_f32_e32 v194, v133
	v_exp_f32_e32 v195, v134
	v_exp_f32_e32 v196, v135
	v_exp_f32_e32 v197, v136
	v_exp_f32_e32 v198, v137
	v_mfma_f32_32x32x16_bf16 v[50:65], v[244:247], v[158:161], v[34:49]
	v_exp_f32_e32 v134, v138
	v_exp_f32_e32 v135, v139
	v_exp_f32_e32 v136, v140
	v_exp_f32_e32 v137, v141
	v_exp_f32_e32 v138, v142
	v_exp_f32_e32 v139, v143
	v_exp_f32_e32 v140, v144
	v_exp_f32_e32 v141, v145
	s_waitcnt lgkmcnt(1)
	v_mfma_f32_32x32x16_bf16 v[66:81], v[102:105], v[154:157], v[66:81]
	v_exp_f32_e32 v142, v82
	v_exp_f32_e32 v143, v83
	v_exp_f32_e32 v144, v84
	v_exp_f32_e32 v145, v85
	v_exp_f32_e32 v199, v86
	v_exp_f32_e32 v200, v87
	v_exp_f32_e32 v201, v88
	v_exp_f32_e32 v202, v89
	s_waitcnt lgkmcnt(0)
	v_mfma_f32_32x32x16_bf16 v[50:65], v[106:109], v[154:157], v[50:65]
	v_exp_f32_e32 v203, v90
	v_exp_f32_e32 v204, v91
	v_exp_f32_e32 v205, v92
	v_exp_f32_e32 v206, v93
	v_exp_f32_e32 v207, v94
	v_exp_f32_e32 v208, v95
	v_exp_f32_e32 v209, v96
	v_exp_f32_e32 v210, v97
	s_cmp_gt_i32 s24, 2
	s_cselect_b32 s27, -3, 2
	s_add_i32 s27, s27, s24
	s_mulk_i32 s27, 0x2400
	v_add_u32_e32 v82, s27, v182
	s_mov_b32 s27, 0x18950000
	s_waitcnt vmcnt(3)
	ds_write_b128 v182, v[146:149] offset:18432
	s_waitcnt vmcnt(2)
	ds_write_b128 v82, v[150:153] offset:36864
	s_add_i32 s92, s23, -4
	s_lshl_b32 s92, s92, 13
	s_add_u32 vcc_lo, s100, s92
	s_addc_u32 vcc_hi, s101, 0
	global_load_dwordx4 v[126:129], v248, vcc
	s_lshl_b32 s92, s25, 7
	s_add_u32 vcc_lo, s98, s92
	s_addc_u32 vcc_hi, s99, 0
	global_load_dwordx4 v[122:125], v249, vcc
	v_add_u32_e32 v111, s26, v163
	v_add_f32_e32 v1, v1, v110
	ds_read_b128 v[240:243], v165 offset:9216
	ds_read_b128 v[244:247], v165 offset:13824
	ds_read_b128 v[82:85], v111 offset:41472
	ds_read_b128 v[86:89], v111 offset:36864
	ds_read_b128 v[90:93], v111 offset:36896
	ds_read_b128 v[94:97], v111 offset:41504
	ds_read_b128 v[98:101], v111 offset:36928
	ds_read_b128 v[102:105], v111 offset:41536
	ds_read_b128 v[106:109], v111 offset:36960
	ds_read_b128 v[110:113], v111 offset:41568
	s_add_i32 s26, s24, 1
	s_setprio 1
	v_cvt_pk_bf16_f32 v130, v185, v186
	v_cvt_pk_bf16_f32 v131, v187, v194
	v_cvt_pk_bf16_f32 v132, v195, v196
	v_cvt_pk_bf16_f32 v133, v197, v198
	s_waitcnt lgkmcnt(6)
	s_nop 0
	v_mfma_f32_32x32x16_bf16 v[18:33], v[86:89], v[130:133], v[18:33]
	v_add_f32_e32 v146, v185, v186
	v_add_f32_e32 v146, v146, v187
	v_add_f32_e32 v146, v146, v194
	s_nop 0
	v_mfma_f32_32x32x16_bf16 v[2:17], v[82:85], v[130:133], v[2:17]
	v_cvt_pk_bf16_f32 v86, v134, v135
	v_cvt_pk_bf16_f32 v87, v136, v137
	v_cvt_pk_bf16_f32 v88, v138, v139
	v_cvt_pk_bf16_f32 v89, v140, v141
	v_add_f32_e32 v146, v146, v195
	v_add_f32_e32 v146, v146, v196
	v_add_f32_e32 v146, v146, v197
	v_add_f32_e32 v146, v146, v198
	s_waitcnt lgkmcnt(5)
	v_mfma_f32_32x32x16_bf16 v[18:33], v[90:93], v[86:89], v[18:33]
	v_add_f32_e32 v146, v146, v134
	v_add_f32_e32 v146, v146, v135
	v_add_f32_e32 v146, v146, v136
	v_add_f32_e32 v146, v146, v137
	s_waitcnt lgkmcnt(4)
	v_mfma_f32_32x32x16_bf16 v[2:17], v[94:97], v[86:89], v[2:17]
	v_cvt_pk_bf16_f32 v82, v142, v143
	v_cvt_pk_bf16_f32 v83, v144, v145
	v_cvt_pk_bf16_f32 v84, v199, v200
	v_cvt_pk_bf16_f32 v85, v201, v202
	v_add_f32_e32 v146, v146, v138
	v_add_f32_e32 v146, v146, v139
	v_add_f32_e32 v146, v146, v140
	v_add_f32_e32 v146, v146, v141
	s_waitcnt lgkmcnt(3)
	v_mfma_f32_32x32x16_bf16 v[18:33], v[98:101], v[82:85], v[18:33]
	v_add_f32_e32 v146, v146, v142
	v_add_f32_e32 v146, v146, v143
	v_add_f32_e32 v146, v146, v144
	v_add_f32_e32 v146, v146, v145
	s_waitcnt lgkmcnt(2)
	v_mfma_f32_32x32x16_bf16 v[2:17], v[102:105], v[82:85], v[2:17]
	v_cvt_pk_bf16_f32 v86, v203, v204
	v_cvt_pk_bf16_f32 v87, v205, v206
	v_cvt_pk_bf16_f32 v88, v207, v208
	v_cvt_pk_bf16_f32 v89, v209, v210
	v_add_f32_e32 v146, v146, v199
	v_add_f32_e32 v146, v146, v200
	v_add_f32_e32 v146, v146, v201
	v_add_f32_e32 v146, v146, v202
	s_waitcnt lgkmcnt(1)
	v_mfma_f32_32x32x16_bf16 v[18:33], v[106:109], v[86:89], v[18:33]
	v_add_f32_e32 v146, v146, v203
	v_add_f32_e32 v146, v146, v204
	v_add_f32_e32 v146, v146, v205
	v_add_f32_e32 v146, v146, v206
	s_waitcnt lgkmcnt(0)
	v_mfma_f32_32x32x16_bf16 v[2:17], v[110:113], v[86:89], v[2:17]
	v_add_f32_e32 v146, v146, v207
	v_add_f32_e32 v146, v146, v208
	v_add_f32_e32 v146, v146, v209
	v_add_f32_e32 v146, v146, v210
	s_setprio 0
	ds_read_b128 v[130:133], v165 offset:9248
	ds_read_b128 v[138:141], v165 offset:13856
	s_cmp_lg_u32 s24, 4
	s_cselect_b32 s24, s26, 0
	s_waitcnt lgkmcnt(2)
	v_mfma_f32_32x32x16_bf16 v[98:113], v[240:243], v[158:161], v[34:49]
	v_exp_f32_e32 v142, v66
	v_exp_f32_e32 v143, v67
	v_exp_f32_e32 v144, v68
	v_exp_f32_e32 v145, v69
	v_exp_f32_e32 v147, v70
	v_exp_f32_e32 v148, v71
	v_exp_f32_e32 v149, v72
	v_exp_f32_e32 v150, v73
	s_waitcnt lgkmcnt(1)
	v_mfma_f32_32x32x16_bf16 v[82:97], v[244:247], v[158:161], v[34:49]
	v_exp_f32_e32 v151, v74
	v_exp_f32_e32 v152, v75
	v_exp_f32_e32 v153, v76
	v_exp_f32_e32 v178, v77
	v_exp_f32_e32 v134, v78
	v_exp_f32_e32 v135, v79
	v_exp_f32_e32 v136, v80
	v_exp_f32_e32 v137, v81
	v_mfma_f32_32x32x16_bf16 v[98:113], v[130:133], v[154:157], v[98:113]
	v_exp_f32_e32 v179, v50
	v_exp_f32_e32 v185, v51
	v_exp_f32_e32 v186, v52
	v_exp_f32_e32 v187, v53
	v_exp_f32_e32 v194, v54
	v_exp_f32_e32 v195, v55
	v_exp_f32_e32 v196, v56
	v_exp_f32_e32 v197, v57
	s_waitcnt lgkmcnt(0)
	v_mfma_f32_32x32x16_bf16 v[82:97], v[138:141], v[154:157], v[82:97]
	v_exp_f32_e32 v198, v58
	v_exp_f32_e32 v199, v59
	v_exp_f32_e32 v200, v60
	v_exp_f32_e32 v201, v61
	v_exp_f32_e32 v138, v62
	v_exp_f32_e32 v139, v63
	v_exp_f32_e32 v140, v64
	v_exp_f32_e32 v141, v65
	s_cmp_gt_i32 s24, 2
	s_cselect_b32 s25, -3, 2
	s_add_i32 s25, s25, s24
	s_mulk_i32 s25, 0x2400
	v_add_u32_e32 v50, s25, v182
	s_add_i32 s25, s24, 1
	s_cmp_lg_u32 s24, 4
	s_cselect_b32 s25, s25, 0
	s_add_i32 s24, s23, -3
	s_min_u32 s26, s24, s13
	s_lshl_b32 s92, s26, 13
	s_waitcnt vmcnt(3)
	ds_write_b128 v182, v[118:121] offset:27648
	s_waitcnt vmcnt(2)
	ds_write_b128 v50, v[114:117] offset:36864
	s_add_u32 vcc_lo, s100, s92
	s_addc_u32 vcc_hi, s101, 0
	global_load_dwordx4 v[118:121], v248, vcc
	s_add_i32 s92, s23, -4
	s_lshl_b32 s92, s92, 7
	s_add_u32 vcc_lo, s98, s92
	s_addc_u32 vcc_hi, s99, 0
	global_load_dwordx4 v[114:117], v249, vcc
	s_mul_i32 s27, s25, 0x2400
	s_add_i32 s28, s27, 0xffffdc00
	s_cmp_lg_u32 s25, 0
	s_cselect_b32 s28, s28, 0x9000
	v_add_u32_e32 v78, s28, v163
	ds_read_b128 v[50:53], v78 offset:36864
	ds_read_b128 v[54:57], v78 offset:36896
	ds_read_b128 v[58:61], v78 offset:41472
	ds_read_b128 v[62:65], v78 offset:41504
	ds_read_b128 v[66:69], v78 offset:36928
	ds_read_b128 v[70:73], v78 offset:36960
	ds_read_b128 v[74:77], v78 offset:41536
	ds_read_b128 v[78:81], v78 offset:41568
	s_setprio 3
	v_cvt_pk_bf16_f32 v130, v142, v143
	v_cvt_pk_bf16_f32 v131, v144, v145
	v_cvt_pk_bf16_f32 v132, v147, v148
	v_cvt_pk_bf16_f32 v133, v149, v150
	s_waitcnt lgkmcnt(7)
	s_nop 0
	v_mfma_f32_32x32x16_bf16 v[18:33], v[50:53], v[130:133], v[18:33]
	v_add_f32_e32 v176, v142, v143
	v_add_f32_e32 v176, v176, v144
	v_add_f32_e32 v176, v176, v145
	s_waitcnt lgkmcnt(5)
	v_mfma_f32_32x32x16_bf16 v[2:17], v[58:61], v[130:133], v[2:17]
	v_cvt_pk_bf16_f32 v50, v151, v152
	v_cvt_pk_bf16_f32 v51, v153, v178
	v_cvt_pk_bf16_f32 v52, v134, v135
	v_cvt_pk_bf16_f32 v53, v136, v137
	v_add_f32_e32 v176, v176, v147
	v_add_f32_e32 v176, v176, v148
	v_add_f32_e32 v176, v176, v149
	v_add_f32_e32 v176, v176, v150
	s_nop 0
	v_mfma_f32_32x32x16_bf16 v[18:33], v[54:57], v[50:53], v[18:33]
	v_add_f32_e32 v176, v176, v151
	v_add_f32_e32 v176, v176, v152
	v_add_f32_e32 v176, v176, v153
	v_add_f32_e32 v176, v176, v178
	s_waitcnt lgkmcnt(4)
	v_mfma_f32_32x32x16_bf16 v[2:17], v[62:65], v[50:53], v[2:17]
	v_cvt_pk_bf16_f32 v54, v179, v185
	v_cvt_pk_bf16_f32 v55, v186, v187
	v_cvt_pk_bf16_f32 v56, v194, v195
	v_cvt_pk_bf16_f32 v57, v196, v197
	v_add_f32_e32 v176, v176, v134
	v_add_f32_e32 v176, v176, v135
	v_add_f32_e32 v176, v176, v136
	v_add_f32_e32 v176, v176, v137
	s_waitcnt lgkmcnt(3)
	v_mfma_f32_32x32x16_bf16 v[18:33], v[66:69], v[54:57], v[18:33]
	v_add_f32_e32 v176, v176, v179
	v_add_f32_e32 v176, v176, v185
	v_add_f32_e32 v176, v176, v186
	v_add_f32_e32 v176, v176, v187
	s_waitcnt lgkmcnt(1)
	v_mfma_f32_32x32x16_bf16 v[2:17], v[74:77], v[54:57], v[2:17]
	v_cvt_pk_bf16_f32 v50, v198, v199
	v_cvt_pk_bf16_f32 v51, v200, v201
	v_cvt_pk_bf16_f32 v52, v138, v139
	v_cvt_pk_bf16_f32 v53, v140, v141
	v_add_f32_e32 v176, v176, v194
	v_add_f32_e32 v176, v176, v195
	v_add_f32_e32 v176, v176, v196
	v_add_f32_e32 v176, v176, v197
	s_nop 0
	v_mfma_f32_32x32x16_bf16 v[18:33], v[70:73], v[50:53], v[18:33]
	v_add_f32_e32 v176, v176, v198
	v_add_f32_e32 v176, v176, v199
	v_add_f32_e32 v176, v176, v200
	v_add_f32_e32 v176, v176, v201
	s_waitcnt lgkmcnt(0)
	v_mfma_f32_32x32x16_bf16 v[2:17], v[78:81], v[50:53], v[2:17]
	v_add_f32_e32 v176, v176, v138
	v_add_f32_e32 v176, v176, v139
	v_add_f32_e32 v176, v176, v140
	v_add_f32_e32 v176, v176, v141
	s_setprio 2
	s_waitcnt lgkmcnt(0)
	s_barrier
	ds_read_b128 v[240:243], v165 offset:18432
	ds_read_b128 v[244:247], v165 offset:23040
	ds_read_b128 v[134:137], v165 offset:18464
	ds_read_b128 v[138:141], v165 offset:23072
	v_add_f32_e32 v1, v1, v146
	s_waitcnt lgkmcnt(2)
	v_mfma_f32_32x32x16_bf16 v[66:81], v[240:243], v[158:161], v[34:49]
	v_exp_f32_e32 v142, v98
	v_exp_f32_e32 v143, v99
	v_exp_f32_e32 v144, v100
	v_exp_f32_e32 v145, v101
	v_exp_f32_e32 v146, v102
	v_exp_f32_e32 v147, v103
	v_exp_f32_e32 v148, v104
	v_exp_f32_e32 v149, v105
	v_mfma_f32_32x32x16_bf16 v[50:65], v[244:247], v[158:161], v[34:49]
	v_exp_f32_e32 v150, v106
	v_exp_f32_e32 v151, v107
	v_exp_f32_e32 v152, v108
	v_exp_f32_e32 v153, v109
	v_exp_f32_e32 v177, v110
	v_exp_f32_e32 v178, v111
	v_exp_f32_e32 v179, v112
	v_exp_f32_e32 v185, v113
	s_waitcnt lgkmcnt(1)
	v_mfma_f32_32x32x16_bf16 v[66:81], v[134:137], v[154:157], v[66:81]
	v_exp_f32_e32 v186, v82
	v_exp_f32_e32 v187, v83
	v_exp_f32_e32 v194, v84
	v_exp_f32_e32 v195, v85
	v_exp_f32_e32 v134, v86
	v_exp_f32_e32 v135, v87
	v_exp_f32_e32 v136, v88
	v_exp_f32_e32 v137, v89
	s_waitcnt lgkmcnt(0)
	v_mfma_f32_32x32x16_bf16 v[50:65], v[138:141], v[154:157], v[50:65]
	v_exp_f32_e32 v196, v90
	v_exp_f32_e32 v197, v91
	v_exp_f32_e32 v198, v92
	v_exp_f32_e32 v199, v93
	v_exp_f32_e32 v138, v94
	v_exp_f32_e32 v139, v95
	v_exp_f32_e32 v140, v96
	v_exp_f32_e32 v141, v97
	s_cmp_gt_i32 s25, 2
	s_cselect_b32 s28, -3, 2
	s_waitcnt vmcnt(3)
	ds_write_b128 v182, v[126:129]
	s_add_i32 s28, s28, s25
	v_add_u32_e32 v126, s27, v163
	s_add_i32 s27, s23, -2
	s_mulk_i32 s28, 0x2400
	s_min_u32 s27, s27, s13
	v_add_u32_e32 v82, s28, v182
	s_lshl_b32 s92, s27, 13
	s_waitcnt vmcnt(2)
	ds_write_b128 v82, v[122:125] offset:36864
	ds_read_b128 v[240:243], v165 offset:27648
	ds_read_b128 v[244:247], v165 offset:32256
	ds_read_b128 v[82:85], v126 offset:41472
	ds_read_b128 v[86:89], v126 offset:36864
	ds_read_b128 v[90:93], v126 offset:36896
	ds_read_b128 v[94:97], v126 offset:41504
	ds_read_b128 v[106:109], v126 offset:36928
	ds_read_b128 v[110:113], v126 offset:41536
	ds_read_b128 v[122:125], v126 offset:36960
	ds_read_b128 v[126:129], v126 offset:41568
	s_add_u32 vcc_lo, s100, s92
	s_addc_u32 vcc_hi, s101, 0
	global_load_dwordx4 v[98:101], v248, vcc
	s_lshl_b32 s92, s26, 7
	s_add_u32 vcc_lo, s98, s92
	s_addc_u32 vcc_hi, s99, 0
	global_load_dwordx4 v[102:105], v249, vcc
	v_add_f32_e32 v1, v1, v176
	s_add_i32 s28, s25, 1
	s_setprio 1
	v_cvt_pk_bf16_f32 v130, v142, v143
	v_cvt_pk_bf16_f32 v131, v144, v145
	v_cvt_pk_bf16_f32 v132, v146, v147
	v_cvt_pk_bf16_f32 v133, v148, v149
	s_waitcnt lgkmcnt(6)
	s_nop 0
	v_mfma_f32_32x32x16_bf16 v[18:33], v[86:89], v[130:133], v[18:33]
	v_add_f32_e32 v176, v142, v143
	v_add_f32_e32 v176, v176, v144
	v_add_f32_e32 v176, v176, v145
	s_nop 0
	v_mfma_f32_32x32x16_bf16 v[2:17], v[82:85], v[130:133], v[2:17]
	v_cvt_pk_bf16_f32 v86, v150, v151
	v_cvt_pk_bf16_f32 v87, v152, v153
	v_cvt_pk_bf16_f32 v88, v177, v178
	v_cvt_pk_bf16_f32 v89, v179, v185
	v_add_f32_e32 v176, v176, v146
	v_add_f32_e32 v176, v176, v147
	v_add_f32_e32 v176, v176, v148
	v_add_f32_e32 v176, v176, v149
	s_waitcnt lgkmcnt(5)
	v_mfma_f32_32x32x16_bf16 v[18:33], v[90:93], v[86:89], v[18:33]
	v_add_f32_e32 v176, v176, v150
	v_add_f32_e32 v176, v176, v151
	v_add_f32_e32 v176, v176, v152
	v_add_f32_e32 v176, v176, v153
	s_waitcnt lgkmcnt(4)
	v_mfma_f32_32x32x16_bf16 v[2:17], v[94:97], v[86:89], v[2:17]
	v_cvt_pk_bf16_f32 v82, v186, v187
	v_cvt_pk_bf16_f32 v83, v194, v195
	v_cvt_pk_bf16_f32 v84, v134, v135
	v_cvt_pk_bf16_f32 v85, v136, v137
	v_add_f32_e32 v176, v176, v177
	v_add_f32_e32 v176, v176, v178
	v_add_f32_e32 v176, v176, v179
	v_add_f32_e32 v176, v176, v185
	s_waitcnt lgkmcnt(3)
	v_mfma_f32_32x32x16_bf16 v[18:33], v[106:109], v[82:85], v[18:33]
	v_add_f32_e32 v176, v176, v186
	v_add_f32_e32 v176, v176, v187
	v_add_f32_e32 v176, v176, v194
	v_add_f32_e32 v176, v176, v195
	s_waitcnt lgkmcnt(2)
	v_mfma_f32_32x32x16_bf16 v[2:17], v[110:113], v[82:85], v[2:17]
	v_cvt_pk_bf16_f32 v86, v196, v197
	v_cvt_pk_bf16_f32 v87, v198, v199
	v_cvt_pk_bf16_f32 v88, v138, v139
	v_cvt_pk_bf16_f32 v89, v140, v141
	v_add_f32_e32 v176, v176, v134
	v_add_f32_e32 v176, v176, v135
	v_add_f32_e32 v176, v176, v136
	v_add_f32_e32 v176, v176, v137
	s_waitcnt lgkmcnt(1)
	v_mfma_f32_32x32x16_bf16 v[18:33], v[122:125], v[86:89], v[18:33]
	v_add_f32_e32 v176, v176, v196
	v_add_f32_e32 v176, v176, v197
	v_add_f32_e32 v176, v176, v198
	v_add_f32_e32 v176, v176, v199
	s_waitcnt lgkmcnt(0)
	v_mfma_f32_32x32x16_bf16 v[2:17], v[126:129], v[86:89], v[2:17]
	v_add_f32_e32 v176, v176, v138
	v_add_f32_e32 v176, v176, v139
	v_add_f32_e32 v176, v176, v140
	v_add_f32_e32 v176, v176, v141
	s_setprio 0
	ds_read_b128 v[106:109], v165 offset:27680
	ds_read_b128 v[122:125], v165 offset:32288
	s_cmp_lg_u32 s25, 4
	s_cselect_b32 s25, s28, 0
	s_waitcnt lgkmcnt(2)
	v_mfma_f32_32x32x16_bf16 v[138:153], v[240:243], v[158:161], v[34:49]
	v_exp_f32_e32 v126, v66
	v_exp_f32_e32 v127, v67
	v_exp_f32_e32 v128, v68
	v_exp_f32_e32 v129, v69
	v_exp_f32_e32 v130, v70
	v_exp_f32_e32 v131, v71
	v_exp_f32_e32 v132, v72
	v_exp_f32_e32 v133, v73
	s_waitcnt lgkmcnt(1)
	v_mfma_f32_32x32x16_bf16 v[82:97], v[244:247], v[158:161], v[34:49]
	v_exp_f32_e32 v134, v74
	v_exp_f32_e32 v135, v75
	v_exp_f32_e32 v136, v76
	v_exp_f32_e32 v137, v77
	v_exp_f32_e32 v177, v78
	v_exp_f32_e32 v178, v79
	v_exp_f32_e32 v179, v80
	v_exp_f32_e32 v185, v81
	v_mfma_f32_32x32x16_bf16 v[138:153], v[106:109], v[154:157], v[138:153]
	v_exp_f32_e32 v80, v50
	v_exp_f32_e32 v81, v51
	v_exp_f32_e32 v186, v52
	v_exp_f32_e32 v187, v53
	v_exp_f32_e32 v194, v54
	v_exp_f32_e32 v195, v55
	v_exp_f32_e32 v196, v56
	v_exp_f32_e32 v197, v57
	s_waitcnt lgkmcnt(0)
	v_mfma_f32_32x32x16_bf16 v[82:97], v[122:125], v[154:157], v[82:97]
	v_exp_f32_e32 v198, v58
	v_exp_f32_e32 v199, v59
	v_exp_f32_e32 v200, v60
	v_exp_f32_e32 v201, v61
	v_exp_f32_e32 v122, v62
	v_exp_f32_e32 v123, v63
	v_exp_f32_e32 v124, v64
	v_exp_f32_e32 v125, v65
	s_cmp_gt_i32 s25, 2
	s_cselect_b32 s26, -3, 2
	s_add_i32 s26, s26, s25
	s_mulk_i32 s26, 0x2400
	v_add_u32_e32 v50, s26, v182
	s_add_i32 s26, s25, 1
	s_cmp_lg_u32 s25, 4
	s_cselect_b32 s25, s26, 0
	s_add_i32 s26, s23, -1
	s_min_u32 s26, s26, s13
	s_lshl_b32 s92, s26, 13
	s_waitcnt vmcnt(3)
	ds_write_b128 v182, v[118:121] offset:9216
	s_waitcnt vmcnt(2)
	ds_write_b128 v50, v[114:117] offset:36864
	s_add_u32 vcc_lo, s100, s92
	s_addc_u32 vcc_hi, s101, 0
	global_load_dwordx4 v[56:59], v248, vcc
	s_lshl_b32 s92, s27, 7
	s_add_u32 vcc_lo, s98, s92
	s_addc_u32 vcc_hi, s99, 0
	global_load_dwordx4 v[52:55], v249, vcc
	s_nop 0
	s_mul_i32 s27, s25, 0x2400
	s_add_i32 s28, s27, 0xffffdc00
	s_cmp_lg_u32 s25, 0
	s_cselect_b32 s28, s28, 0x9000
	v_add_u32_e32 v50, s28, v163
	ds_read_b128 v[60:63], v50 offset:36864
	ds_read_b128 v[64:67], v50 offset:36896
	ds_read_b128 v[68:71], v50 offset:41472
	ds_read_b128 v[72:75], v50 offset:41504
	ds_read_b128 v[76:79], v50 offset:36928
	ds_read_b128 v[106:109], v50 offset:36960
	ds_read_b128 v[110:113], v50 offset:41536
	ds_read_b128 v[114:117], v50 offset:41568
	s_setprio 3
	v_cvt_pk_bf16_f32 v118, v126, v127
	v_cvt_pk_bf16_f32 v119, v128, v129
	v_cvt_pk_bf16_f32 v120, v130, v131
	v_cvt_pk_bf16_f32 v121, v132, v133
	s_waitcnt lgkmcnt(7)
	s_nop 0
	v_mfma_f32_32x32x16_bf16 v[18:33], v[60:63], v[118:121], v[18:33]
	v_add_f32_e32 v50, v126, v127
	v_add_f32_e32 v50, v50, v128
	v_add_f32_e32 v50, v50, v129
	s_waitcnt lgkmcnt(5)
	v_mfma_f32_32x32x16_bf16 v[2:17], v[68:71], v[118:121], v[2:17]
	v_cvt_pk_bf16_f32 v60, v134, v135
	v_cvt_pk_bf16_f32 v61, v136, v137
	v_cvt_pk_bf16_f32 v62, v177, v178
	v_cvt_pk_bf16_f32 v63, v179, v185
	v_add_f32_e32 v50, v50, v130
	v_add_f32_e32 v50, v50, v131
	v_add_f32_e32 v50, v50, v132
	v_add_f32_e32 v50, v50, v133
	s_nop 0
	v_mfma_f32_32x32x16_bf16 v[18:33], v[64:67], v[60:63], v[18:33]
	v_add_f32_e32 v50, v50, v134
	v_add_f32_e32 v50, v50, v135
	v_add_f32_e32 v50, v50, v136
	v_add_f32_e32 v50, v50, v137
	s_waitcnt lgkmcnt(4)
	v_mfma_f32_32x32x16_bf16 v[2:17], v[72:75], v[60:63], v[2:17]
	v_cvt_pk_bf16_f32 v64, v80, v81
	v_cvt_pk_bf16_f32 v65, v186, v187
	v_cvt_pk_bf16_f32 v66, v194, v195
	v_cvt_pk_bf16_f32 v67, v196, v197
	v_add_f32_e32 v50, v50, v177
	v_add_f32_e32 v50, v50, v178
	v_add_f32_e32 v50, v50, v179
	v_add_f32_e32 v50, v50, v185
	s_waitcnt lgkmcnt(3)
	v_mfma_f32_32x32x16_bf16 v[18:33], v[76:79], v[64:67], v[18:33]
	v_add_f32_e32 v50, v50, v80
	v_add_f32_e32 v50, v50, v81
	v_add_f32_e32 v50, v50, v186
	v_add_f32_e32 v50, v50, v187
	s_waitcnt lgkmcnt(1)
	v_mfma_f32_32x32x16_bf16 v[2:17], v[110:113], v[64:67], v[2:17]
	v_cvt_pk_bf16_f32 v60, v198, v199
	v_cvt_pk_bf16_f32 v61, v200, v201
	v_cvt_pk_bf16_f32 v62, v122, v123
	v_cvt_pk_bf16_f32 v63, v124, v125
	v_add_f32_e32 v50, v50, v194
	v_add_f32_e32 v50, v50, v195
	v_add_f32_e32 v50, v50, v196
	v_add_f32_e32 v50, v50, v197
	s_nop 0
	v_mfma_f32_32x32x16_bf16 v[18:33], v[106:109], v[60:63], v[18:33]
	v_add_f32_e32 v50, v50, v198
	v_add_f32_e32 v50, v50, v199
	v_add_f32_e32 v50, v50, v200
	v_add_f32_e32 v50, v50, v201
	s_waitcnt lgkmcnt(0)
	v_mfma_f32_32x32x16_bf16 v[2:17], v[114:117], v[60:63], v[2:17]
	v_add_f32_e32 v50, v50, v122
	v_add_f32_e32 v50, v50, v123
	v_add_f32_e32 v50, v50, v124
	v_add_f32_e32 v50, v50, v125
	s_setprio 2
	s_waitcnt lgkmcnt(0)
	s_barrier
	ds_read_b128 v[240:243], v165
	ds_read_b128 v[244:247], v165 offset:4608
	ds_read_b128 v[68:71], v165 offset:32
	ds_read_b128 v[72:75], v165 offset:4640
	v_add_f32_e32 v1, v1, v176
	s_waitcnt lgkmcnt(2)
	v_mfma_f32_32x32x16_bf16 v[122:137], v[240:243], v[158:161], v[34:49]
	v_exp_f32_e32 v176, v138
	v_exp_f32_e32 v177, v139
	v_exp_f32_e32 v178, v140
	v_exp_f32_e32 v179, v141
	v_exp_f32_e32 v185, v142
	v_exp_f32_e32 v186, v143
	v_exp_f32_e32 v187, v144
	v_exp_f32_e32 v194, v145
	v_mfma_f32_32x32x16_bf16 v[106:121], v[244:247], v[158:161], v[34:49]
	v_exp_f32_e32 v195, v146
	v_exp_f32_e32 v196, v147
	v_exp_f32_e32 v197, v148
	v_exp_f32_e32 v198, v149
	v_exp_f32_e32 v146, v150
	v_exp_f32_e32 v147, v151
	v_exp_f32_e32 v148, v152
	v_exp_f32_e32 v149, v153
	s_waitcnt lgkmcnt(1)
	v_mfma_f32_32x32x16_bf16 v[122:137], v[68:71], v[154:157], v[122:137]
	v_exp_f32_e32 v150, v82
	v_exp_f32_e32 v151, v83
	v_exp_f32_e32 v152, v84
	v_exp_f32_e32 v153, v85
	v_exp_f32_e32 v199, v86
	v_exp_f32_e32 v200, v87
	v_exp_f32_e32 v201, v88
	v_exp_f32_e32 v202, v89
	s_waitcnt lgkmcnt(0)
	v_mfma_f32_32x32x16_bf16 v[106:121], v[72:75], v[154:157], v[106:121]
	v_exp_f32_e32 v203, v90
	v_exp_f32_e32 v204, v91
	v_exp_f32_e32 v205, v92
	v_exp_f32_e32 v206, v93
	v_exp_f32_e32 v207, v94
	v_exp_f32_e32 v208, v95
	v_exp_f32_e32 v209, v96
	v_exp_f32_e32 v210, v97
	v_add_u32_e32 v88, s27, v163
	ds_read_b128 v[240:243], v165 offset:9216
	ds_read_b128 v[244:247], v165 offset:13824
	ds_read_b128 v[60:63], v88 offset:41472
	ds_read_b128 v[64:67], v88 offset:36864
	ds_read_b128 v[68:71], v88 offset:36896
	ds_read_b128 v[72:75], v88 offset:41504
	ds_read_b128 v[76:79], v88 offset:36928
	ds_read_b128 v[80:83], v88 offset:41536
	ds_read_b128 v[84:87], v88 offset:36960
	ds_read_b128 v[88:91], v88 offset:41568
	s_cmp_gt_i32 s25, 2
	s_cselect_b32 s28, -3, 2
	s_add_i32 s28, s28, s25
	s_mulk_i32 s28, 0x2400
	s_min_u32 s27, s23, s13
	v_add_u32_e32 v51, s28, v182
	s_lshl_b32 s92, s27, 13
	s_waitcnt vmcnt(3)
	ds_write_b128 v182, v[98:101] offset:18432
	s_waitcnt vmcnt(2)
	ds_write_b128 v51, v[102:105] offset:36864
	v_add_f32_e32 v1, v1, v50
	s_add_u32 vcc_lo, s100, s92
	s_addc_u32 vcc_hi, s101, 0
	global_load_dwordx4 v[138:141], v248, vcc
	s_lshl_b32 s92, s26, 7
	s_add_u32 vcc_lo, s98, s92
	s_addc_u32 vcc_hi, s99, 0
	global_load_dwordx4 v[142:145], v249, vcc
	s_setprio 1
	v_mov_b32_e32 v51, v122
	v_cvt_pk_bf16_f32 v92, v176, v177
	v_cvt_pk_bf16_f32 v93, v178, v179
	v_cvt_pk_bf16_f32 v94, v185, v186
	v_cvt_pk_bf16_f32 v95, v187, v194
	s_waitcnt lgkmcnt(8)
	s_nop 0
	v_mfma_f32_32x32x16_bf16 v[18:33], v[64:67], v[92:95], v[18:33]
	v_max3_f32 v51, v51, v123, v124
	v_max3_f32 v51, v51, v125, v126
	v_add_f32_e32 v50, v176, v177
	v_add_f32_e32 v50, v50, v178
	v_add_f32_e32 v50, v50, v179
	s_nop 0
	v_mfma_f32_32x32x16_bf16 v[2:17], v[60:63], v[92:95], v[2:17]
	v_cvt_pk_bf16_f32 v64, v195, v196
	v_cvt_pk_bf16_f32 v65, v197, v198
	v_cvt_pk_bf16_f32 v66, v146, v147
	v_cvt_pk_bf16_f32 v67, v148, v149
	v_max3_f32 v51, v51, v127, v128
	v_max3_f32 v51, v51, v129, v130
	v_add_f32_e32 v50, v50, v185
	v_add_f32_e32 v50, v50, v186
	v_add_f32_e32 v50, v50, v187
	v_add_f32_e32 v50, v50, v194
	s_waitcnt lgkmcnt(7)
	v_mfma_f32_32x32x16_bf16 v[18:33], v[68:71], v[64:67], v[18:33]
	v_max3_f32 v51, v51, v131, v132
	v_max3_f32 v51, v51, v133, v134
	v_add_f32_e32 v50, v50, v195
	v_add_f32_e32 v50, v50, v196
	v_add_f32_e32 v50, v50, v197
	v_add_f32_e32 v50, v50, v198
	s_waitcnt lgkmcnt(6)
	v_mfma_f32_32x32x16_bf16 v[2:17], v[72:75], v[64:67], v[2:17]
	v_cvt_pk_bf16_f32 v60, v150, v151
	v_cvt_pk_bf16_f32 v61, v152, v153
	v_cvt_pk_bf16_f32 v62, v199, v200
	v_cvt_pk_bf16_f32 v63, v201, v202
	v_max3_f32 v51, v51, v135, v136
	v_max3_f32 v51, v51, v137, v106
	v_add_f32_e32 v50, v50, v146
	v_add_f32_e32 v50, v50, v147
	v_add_f32_e32 v50, v50, v148
	v_add_f32_e32 v50, v50, v149
	s_waitcnt lgkmcnt(5)
	v_mfma_f32_32x32x16_bf16 v[18:33], v[76:79], v[60:63], v[18:33]
	v_max3_f32 v51, v51, v107, v108
	v_max3_f32 v51, v51, v109, v110
	v_add_f32_e32 v50, v50, v150
	v_add_f32_e32 v50, v50, v151
	v_add_f32_e32 v50, v50, v152
	v_add_f32_e32 v50, v50, v153
	s_waitcnt lgkmcnt(4)
	v_mfma_f32_32x32x16_bf16 v[2:17], v[80:83], v[60:63], v[2:17]
	v_cvt_pk_bf16_f32 v64, v203, v204
	v_cvt_pk_bf16_f32 v65, v205, v206
	v_cvt_pk_bf16_f32 v66, v207, v208
	v_cvt_pk_bf16_f32 v67, v209, v210
	v_max3_f32 v51, v51, v111, v112
	v_max3_f32 v51, v51, v113, v114
	v_add_f32_e32 v50, v50, v199
	v_add_f32_e32 v50, v50, v200
	v_add_f32_e32 v50, v50, v201
	v_add_f32_e32 v50, v50, v202
	s_waitcnt lgkmcnt(3)
	v_mfma_f32_32x32x16_bf16 v[18:33], v[84:87], v[64:67], v[18:33]
	v_max3_f32 v51, v51, v115, v116
	v_max3_f32 v51, v51, v117, v118
	v_add_f32_e32 v50, v50, v203
	v_add_f32_e32 v50, v50, v204
	v_add_f32_e32 v50, v50, v205
	v_add_f32_e32 v50, v50, v206
	s_waitcnt lgkmcnt(2)
	v_mfma_f32_32x32x16_bf16 v[2:17], v[88:91], v[64:67], v[2:17]
	v_max3_f32 v51, v51, v119, v120
	v_max3_f32 v51, v51, v121, v121
	v_add_f32_e32 v50, v50, v207
	v_add_f32_e32 v50, v50, v208
	v_add_f32_e32 v50, v50, v209
	v_add_f32_e32 v50, v50, v210
	s_setprio 0
	ds_read_b128 v[146:149], v165 offset:9248
	ds_read_b128 v[60:63], v165 offset:13856
	v_add_f32_e32 v50, v1, v50
	v_mov_b32_e32 v1, v51
	s_nop 1
	v_permlane32_swap_b32_e32 v51, v1
	v_max_f32_e32 v1, v1, v1
	v_max_f32_e32 v51, v51, v51
	v_max_f32_e32 v1, v51, v1
	v_cmp_lt_f32_e32 vcc, s52, v1
	s_cbranch_vccz .LBB0_643
	v_max_f32_e32 v1, v1, v1
	v_max_f32_e32 v68, 0, v1
	v_add_f32_e32 v183, v183, v68
	v_xor_b32_e32 v34, 0x80000000, v183
	v_pk_add_f32 v[122:123], v[122:123], v[68:69] op_sel_hi:[1,0] neg_lo:[0,1] neg_hi:[0,1]
	v_pk_add_f32 v[106:107], v[106:107], v[68:69] op_sel_hi:[1,0] neg_lo:[0,1] neg_hi:[0,1]
	v_pk_add_f32 v[124:125], v[124:125], v[68:69] op_sel_hi:[1,0] neg_lo:[0,1] neg_hi:[0,1]
	v_pk_add_f32 v[108:109], v[108:109], v[68:69] op_sel_hi:[1,0] neg_lo:[0,1] neg_hi:[0,1]
	v_pk_add_f32 v[126:127], v[126:127], v[68:69] op_sel_hi:[1,0] neg_lo:[0,1] neg_hi:[0,1]
	v_pk_add_f32 v[110:111], v[110:111], v[68:69] op_sel_hi:[1,0] neg_lo:[0,1] neg_hi:[0,1]
	v_pk_add_f32 v[128:129], v[128:129], v[68:69] op_sel_hi:[1,0] neg_lo:[0,1] neg_hi:[0,1]
	v_pk_add_f32 v[112:113], v[112:113], v[68:69] op_sel_hi:[1,0] neg_lo:[0,1] neg_hi:[0,1]
	v_pk_add_f32 v[130:131], v[130:131], v[68:69] op_sel_hi:[1,0] neg_lo:[0,1] neg_hi:[0,1]
	v_pk_add_f32 v[114:115], v[114:115], v[68:69] op_sel_hi:[1,0] neg_lo:[0,1] neg_hi:[0,1]
	v_pk_add_f32 v[132:133], v[132:133], v[68:69] op_sel_hi:[1,0] neg_lo:[0,1] neg_hi:[0,1]
	v_pk_add_f32 v[116:117], v[116:117], v[68:69] op_sel_hi:[1,0] neg_lo:[0,1] neg_hi:[0,1]
	v_pk_add_f32 v[134:135], v[134:135], v[68:69] op_sel_hi:[1,0] neg_lo:[0,1] neg_hi:[0,1]
	v_pk_add_f32 v[118:119], v[118:119], v[68:69] op_sel_hi:[1,0] neg_lo:[0,1] neg_hi:[0,1]
	v_pk_add_f32 v[136:137], v[136:137], v[68:69] op_sel_hi:[1,0] neg_lo:[0,1] neg_hi:[0,1]
	v_pk_add_f32 v[120:121], v[120:121], v[68:69] op_sel_hi:[1,0] neg_lo:[0,1] neg_hi:[0,1]
	v_exp_f32_e64 v68, -v68
	v_mov_b32_e32 v35, v34
	v_mov_b32_e32 v36, v34
	v_mov_b32_e32 v37, v34
	v_mov_b32_e32 v38, v34
	v_mov_b32_e32 v39, v34
	v_mov_b32_e32 v40, v34
	v_mov_b32_e32 v41, v34
	v_mov_b32_e32 v42, v34
	v_mov_b32_e32 v43, v34
	v_mov_b32_e32 v44, v34
	v_mov_b32_e32 v45, v34
	v_mov_b32_e32 v46, v34
	v_mov_b32_e32 v47, v34
	v_mov_b32_e32 v48, v34
	v_mov_b32_e32 v49, v34
	s_nop 11
	v_pk_mul_f32 v[32:33], v[32:33], v[68:69] op_sel_hi:[1,0]
	v_pk_mul_f32 v[30:31], v[30:31], v[68:69] op_sel_hi:[1,0]
	v_pk_mul_f32 v[28:29], v[28:29], v[68:69] op_sel_hi:[1,0]
	v_pk_mul_f32 v[26:27], v[26:27], v[68:69] op_sel_hi:[1,0]
	v_pk_mul_f32 v[24:25], v[24:25], v[68:69] op_sel_hi:[1,0]
	v_pk_mul_f32 v[22:23], v[22:23], v[68:69] op_sel_hi:[1,0]
	v_pk_mul_f32 v[20:21], v[20:21], v[68:69] op_sel_hi:[1,0]
	v_pk_mul_f32 v[18:19], v[18:19], v[68:69] op_sel_hi:[1,0]
	v_pk_mul_f32 v[16:17], v[16:17], v[68:69] op_sel_hi:[1,0]
	v_pk_mul_f32 v[14:15], v[14:15], v[68:69] op_sel_hi:[1,0]
	v_pk_mul_f32 v[12:13], v[12:13], v[68:69] op_sel_hi:[1,0]
	v_pk_mul_f32 v[10:11], v[10:11], v[68:69] op_sel_hi:[1,0]
	v_pk_mul_f32 v[8:9], v[8:9], v[68:69] op_sel_hi:[1,0]
	v_pk_mul_f32 v[6:7], v[6:7], v[68:69] op_sel_hi:[1,0]
	v_pk_mul_f32 v[4:5], v[4:5], v[68:69] op_sel_hi:[1,0]
	v_pk_mul_f32 v[2:3], v[2:3], v[68:69] op_sel_hi:[1,0]
	v_mul_f32_e32 v50, v50, v68

.LBB0_661:
	s_add_i32 s26, s13, -7
	s_lshl_b32 s92, s26, 13
	s_add_u32 vcc_lo, s100, s92
	s_addc_u32 vcc_hi, s101, 0
	global_load_dwordx4 v[2:5], v248, vcc
	s_add_i32 s26, s13, -8
	s_lshl_b32 s92, s26, 7
	s_add_u32 vcc_lo, s98, s92
	s_addc_u32 vcc_hi, s99, 0
	global_load_dwordx4 v[6:9], v249, vcc
	s_mul_i32 s28, s27, 0x2400
	s_add_i32 s26, s13, -7
	s_add_i32 s29, s28, 0xffffdc00
	s_cmp_lg_u32 s27, 0
	s_cselect_b32 s29, s29, 0x9000
	v_add_u32_e32 v1, s29, v195
	ds_read_b128 v[10:13], v1 offset:36864
	ds_read_b128 v[66:69], v1 offset:36896
	ds_read_b128 v[70:73], v1 offset:41472
	ds_read_b128 v[74:77], v1 offset:41504
	ds_read_b128 v[128:131], v1 offset:36928
	ds_read_b128 v[132:135], v1 offset:36960
	ds_read_b128 v[148:151], v1 offset:41536
	ds_read_b128 v[160:163], v1 offset:41568
	s_setprio 3
	v_cvt_pk_bf16_f32 v210, v116, v117
	v_cvt_pk_bf16_f32 v211, v118, v119
	v_cvt_pk_bf16_f32 v212, v112, v113
	v_cvt_pk_bf16_f32 v213, v114, v115
	s_waitcnt lgkmcnt(7)
	s_nop 0
	v_mfma_f32_32x32x16_bf16 v[16:31], v[10:13], v[210:213], v[16:31]
	v_add_f32_e32 v1, v116, v117
	v_add_f32_e32 v1, v1, v118
	v_add_f32_e32 v1, v1, v119
	s_waitcnt lgkmcnt(5)
	v_mfma_f32_32x32x16_bf16 v[32:47], v[70:73], v[210:213], v[32:47]
	v_cvt_pk_bf16_f32 v10, v187, v186
	v_cvt_pk_bf16_f32 v11, v185, v184
	v_cvt_pk_bf16_f32 v12, v147, v146
	v_cvt_pk_bf16_f32 v13, v145, v144
	v_add_f32_e32 v1, v1, v112
	v_add_f32_e32 v1, v1, v113
	v_add_f32_e32 v1, v1, v114
	v_add_f32_e32 v1, v1, v115
	s_nop 0
	v_mfma_f32_32x32x16_bf16 v[16:31], v[66:69], v[10:13], v[16:31]
	v_add_f32_e32 v1, v1, v187
	v_add_f32_e32 v1, v1, v186
	v_add_f32_e32 v1, v1, v185
	v_add_f32_e32 v1, v1, v184
	s_waitcnt lgkmcnt(4)
	v_mfma_f32_32x32x16_bf16 v[32:47], v[74:77], v[10:13], v[32:47]
	v_cvt_pk_bf16_f32 v66, v143, v142
	v_cvt_pk_bf16_f32 v67, v141, v140
	v_cvt_pk_bf16_f32 v68, v139, v138
	v_cvt_pk_bf16_f32 v69, v137, v136
	v_add_f32_e32 v1, v1, v147
	v_add_f32_e32 v1, v1, v146
	v_add_f32_e32 v1, v1, v145
	v_add_f32_e32 v1, v1, v144
	s_waitcnt lgkmcnt(3)
	v_mfma_f32_32x32x16_bf16 v[16:31], v[128:131], v[66:69], v[16:31]
	v_add_f32_e32 v1, v1, v143
	v_add_f32_e32 v1, v1, v142
	v_add_f32_e32 v1, v1, v141
	v_add_f32_e32 v1, v1, v140
	s_waitcnt lgkmcnt(1)
	v_mfma_f32_32x32x16_bf16 v[32:47], v[148:151], v[66:69], v[32:47]
	v_cvt_pk_bf16_f32 v10, v123, v122
	v_cvt_pk_bf16_f32 v11, v121, v120
	v_cvt_pk_bf16_f32 v12, v127, v126
	v_cvt_pk_bf16_f32 v13, v125, v124
	v_add_f32_e32 v1, v1, v139
	v_add_f32_e32 v1, v1, v138
	v_add_f32_e32 v1, v1, v137
	v_add_f32_e32 v1, v1, v136
	s_nop 0
	v_mfma_f32_32x32x16_bf16 v[16:31], v[132:135], v[10:13], v[16:31]
	v_add_f32_e32 v1, v1, v123
	v_add_f32_e32 v1, v1, v122
	v_add_f32_e32 v1, v1, v121
	v_add_f32_e32 v1, v1, v120
	s_waitcnt lgkmcnt(0)
	v_mfma_f32_32x32x16_bf16 v[32:47], v[160:163], v[10:13], v[32:47]
	v_add_f32_e32 v1, v1, v127
	v_add_f32_e32 v1, v1, v126
	v_add_f32_e32 v1, v1, v125
	v_add_f32_e32 v1, v1, v124
	s_setprio 2
	s_waitcnt lgkmcnt(0)
	s_barrier
	ds_read_b128 v[240:243], v195 offset:18432
	ds_read_b128 v[244:247], v195 offset:23040
	ds_read_b128 v[66:69], v195 offset:18464
	ds_read_b128 v[74:77], v195 offset:23072
	ds_read_b128 v[144:147], v195 offset:18496
	ds_read_b128 v[148:151], v195 offset:18528
	ds_read_b128 v[160:163], v195 offset:23104
	ds_read_b128 v[184:187], v195 offset:23136
	s_waitcnt lgkmcnt(6)
	v_mfma_f32_32x32x16_bf16 v[128:143], v[240:243], v[180:183], v[48:63]
	v_exp_f32_e32 v166, v96
	v_exp_f32_e32 v167, v97
	v_exp_f32_e32 v210, v98
	v_exp_f32_e32 v211, v99
	s_waitcnt lgkmcnt(5)
	v_mfma_f32_32x32x16_bf16 v[112:127], v[244:247], v[180:183], v[48:63]
	v_exp_f32_e32 v212, v100
	v_exp_f32_e32 v213, v101
	v_exp_f32_e32 v214, v102
	v_exp_f32_e32 v215, v103
	v_mfma_f32_32x32x16_bf16 v[128:143], v[66:69], v[176:179], v[128:143]
	v_exp_f32_e32 v100, v104
	v_exp_f32_e32 v101, v105
	v_exp_f32_e32 v102, v106
	v_exp_f32_e32 v103, v107
	s_waitcnt lgkmcnt(4)
	v_mfma_f32_32x32x16_bf16 v[112:127], v[74:77], v[176:179], v[112:127]
	v_exp_f32_e32 v104, v108
	v_exp_f32_e32 v105, v109
	v_exp_f32_e32 v106, v110
	v_exp_f32_e32 v107, v111
	s_waitcnt lgkmcnt(3)
	v_mfma_f32_32x32x16_bf16 v[128:143], v[144:147], v[172:175], v[128:143]
	v_exp_f32_e32 v108, v80
	v_exp_f32_e32 v109, v81
	v_exp_f32_e32 v110, v82
	v_exp_f32_e32 v111, v83
	s_waitcnt lgkmcnt(1)
	v_mfma_f32_32x32x16_bf16 v[112:127], v[160:163], v[172:175], v[112:127]
	v_exp_f32_e32 v144, v84
	v_exp_f32_e32 v145, v85
	v_exp_f32_e32 v146, v86
	v_exp_f32_e32 v147, v87
	v_mfma_f32_32x32x16_bf16 v[128:143], v[148:151], v[168:171], v[128:143]
	v_exp_f32_e32 v216, v88
	v_exp_f32_e32 v217, v89
	v_exp_f32_e32 v218, v90
	v_exp_f32_e32 v219, v91
	s_waitcnt lgkmcnt(0)
	v_mfma_f32_32x32x16_bf16 v[112:127], v[184:187], v[168:171], v[112:127]
	v_exp_f32_e32 v148, v92
	v_exp_f32_e32 v149, v93
	v_exp_f32_e32 v150, v94
	v_exp_f32_e32 v151, v95
	s_cmp_gt_i32 s27, 2
	s_cselect_b32 s29, -3, 2
	s_add_i32 s29, s29, s27
	v_add_u32_e32 v92, s28, v195
	s_add_i32 s28, s13, -6
	s_mulk_i32 s29, 0x2400
	s_min_u32 s28, s28, s12
	v_add_u32_e32 v10, s29, v208
	s_min_u32 s26, s26, s12
	s_lshl_b32 s92, s28, 13
	s_waitcnt vmcnt(3)
	ds_write_b128 v208, v[152:155]
	s_waitcnt vmcnt(2)
	ds_write_b128 v10, v[156:159] offset:36864
	s_add_u32 vcc_lo, s100, s92
	s_addc_u32 vcc_hi, s101, 0
	global_load_dwordx4 v[10:13], v248, vcc
	s_lshl_b32 s92, s26, 7
	v_add_f32_e32 v1, v64, v1
	ds_read_b128 v[240:243], v195 offset:27648
	ds_read_b128 v[244:247], v195 offset:32256
	ds_read_b128 v[64:67], v92 offset:41472
	ds_read_b128 v[68:71], v92 offset:36864
	ds_read_b128 v[72:75], v92 offset:36896
	ds_read_b128 v[76:79], v92 offset:41504
	ds_read_b128 v[80:83], v92 offset:36928
	ds_read_b128 v[84:87], v92 offset:41536
	ds_read_b128 v[88:91], v92 offset:36960
	ds_read_b128 v[92:95], v92 offset:41568
	s_add_u32 vcc_lo, s98, s92
	s_addc_u32 vcc_hi, s99, 0
	global_load_dwordx4 v[160:163], v249, vcc
	s_add_i32 s29, s27, 1
	s_setprio 1
	v_cvt_pk_bf16_f32 v96, v166, v167
	v_cvt_pk_bf16_f32 v97, v210, v211
	v_cvt_pk_bf16_f32 v98, v212, v213
	v_cvt_pk_bf16_f32 v99, v214, v215
	s_waitcnt lgkmcnt(6)
	s_nop 0
	v_mfma_f32_32x32x16_bf16 v[16:31], v[68:71], v[96:99], v[16:31]
	v_add_f32_e32 v184, v166, v167
	v_add_f32_e32 v184, v184, v210
	v_add_f32_e32 v184, v184, v211
	s_nop 0
	v_mfma_f32_32x32x16_bf16 v[32:47], v[64:67], v[96:99], v[32:47]
	v_cvt_pk_bf16_f32 v68, v100, v101
	v_cvt_pk_bf16_f32 v69, v102, v103
	v_cvt_pk_bf16_f32 v70, v104, v105
	v_cvt_pk_bf16_f32 v71, v106, v107
	v_add_f32_e32 v184, v184, v212
	v_add_f32_e32 v184, v184, v213
	v_add_f32_e32 v184, v184, v214
	v_add_f32_e32 v184, v184, v215
	s_waitcnt lgkmcnt(5)
	v_mfma_f32_32x32x16_bf16 v[16:31], v[72:75], v[68:71], v[16:31]
	v_add_f32_e32 v184, v184, v100
	v_add_f32_e32 v184, v184, v101
	v_add_f32_e32 v184, v184, v102
	v_add_f32_e32 v184, v184, v103
	s_waitcnt lgkmcnt(4)
	v_mfma_f32_32x32x16_bf16 v[32:47], v[76:79], v[68:71], v[32:47]
	v_cvt_pk_bf16_f32 v64, v108, v109
	v_cvt_pk_bf16_f32 v65, v110, v111
	v_cvt_pk_bf16_f32 v66, v144, v145
	v_cvt_pk_bf16_f32 v67, v146, v147
	v_add_f32_e32 v184, v184, v104
	v_add_f32_e32 v184, v184, v105
	v_add_f32_e32 v184, v184, v106
	v_add_f32_e32 v184, v184, v107
	s_waitcnt lgkmcnt(3)
	v_mfma_f32_32x32x16_bf16 v[16:31], v[80:83], v[64:67], v[16:31]
	v_add_f32_e32 v184, v184, v108
	v_add_f32_e32 v184, v184, v109
	v_add_f32_e32 v184, v184, v110
	v_add_f32_e32 v184, v184, v111
	s_waitcnt lgkmcnt(2)
	v_mfma_f32_32x32x16_bf16 v[32:47], v[84:87], v[64:67], v[32:47]
	v_cvt_pk_bf16_f32 v68, v216, v217
	v_cvt_pk_bf16_f32 v69, v218, v219
	v_cvt_pk_bf16_f32 v70, v148, v149
	v_cvt_pk_bf16_f32 v71, v150, v151
	v_add_f32_e32 v184, v184, v144
	v_add_f32_e32 v184, v184, v145
	v_add_f32_e32 v184, v184, v146
	v_add_f32_e32 v184, v184, v147
	s_waitcnt lgkmcnt(1)
	v_mfma_f32_32x32x16_bf16 v[16:31], v[88:91], v[68:71], v[16:31]
	v_add_f32_e32 v184, v184, v216
	v_add_f32_e32 v184, v184, v217
	v_add_f32_e32 v184, v184, v218
	v_add_f32_e32 v184, v184, v219
	s_waitcnt lgkmcnt(0)
	v_mfma_f32_32x32x16_bf16 v[32:47], v[92:95], v[68:71], v[32:47]
	v_add_f32_e32 v184, v184, v148
	v_add_f32_e32 v184, v184, v149
	v_add_f32_e32 v184, v184, v150
	v_add_f32_e32 v184, v184, v151
	s_setprio 0
	ds_read_b128 v[68:71], v195 offset:27680
	ds_read_b128 v[76:79], v195 offset:32288
	ds_read_b128 v[80:83], v195 offset:27712
	ds_read_b128 v[84:87], v195 offset:27744
	ds_read_b128 v[88:91], v195 offset:32320
	ds_read_b128 v[92:95], v195 offset:32352
	s_cmp_lg_u32 s27, 4
	s_cselect_b32 s26, s29, 0
	s_waitcnt lgkmcnt(6)
	v_mfma_f32_32x32x16_bf16 v[144:159], v[240:243], v[180:183], v[48:63]
	v_exp_f32_e32 v166, v128
	v_exp_f32_e32 v167, v129
	v_exp_f32_e32 v185, v130
	v_exp_f32_e32 v186, v131
	s_waitcnt lgkmcnt(5)
	v_mfma_f32_32x32x16_bf16 v[96:111], v[244:247], v[180:183], v[48:63]
	v_exp_f32_e32 v128, v132
	v_exp_f32_e32 v129, v133
	v_exp_f32_e32 v130, v134
	v_exp_f32_e32 v131, v135
	v_mfma_f32_32x32x16_bf16 v[144:159], v[68:71], v[176:179], v[144:159]
	v_exp_f32_e32 v132, v136
	v_exp_f32_e32 v133, v137
	v_exp_f32_e32 v134, v138
	v_exp_f32_e32 v135, v139
	s_waitcnt lgkmcnt(4)
	v_mfma_f32_32x32x16_bf16 v[96:111], v[76:79], v[176:179], v[96:111]
	v_exp_f32_e32 v136, v140
	v_exp_f32_e32 v137, v141
	v_exp_f32_e32 v138, v142
	v_exp_f32_e32 v139, v143
	s_waitcnt lgkmcnt(3)
	v_mfma_f32_32x32x16_bf16 v[144:159], v[80:83], v[172:175], v[144:159]
	v_exp_f32_e32 v140, v112
	v_exp_f32_e32 v141, v113
	v_exp_f32_e32 v142, v114
	v_exp_f32_e32 v143, v115
	s_waitcnt lgkmcnt(1)
	v_mfma_f32_32x32x16_bf16 v[96:111], v[88:91], v[172:175], v[96:111]
	v_exp_f32_e32 v187, v116
	v_exp_f32_e32 v210, v117
	v_exp_f32_e32 v211, v118
	v_exp_f32_e32 v212, v119
	v_mfma_f32_32x32x16_bf16 v[144:159], v[84:87], v[168:171], v[144:159]
	v_exp_f32_e32 v116, v120
	v_exp_f32_e32 v117, v121
	v_exp_f32_e32 v118, v122
	v_exp_f32_e32 v119, v123
	s_waitcnt lgkmcnt(0)
	v_mfma_f32_32x32x16_bf16 v[96:111], v[92:95], v[168:171], v[96:111]
	v_exp_f32_e32 v120, v124
	v_exp_f32_e32 v121, v125
	v_exp_f32_e32 v122, v126
	v_exp_f32_e32 v123, v127
	s_cmp_gt_i32 s26, 2
	s_cselect_b32 s27, -3, 2
	s_add_i32 s27, s27, s26
	s_mulk_i32 s27, 0x2400
	s_waitcnt vmcnt(3)
	ds_write_b128 v208, v[2:5] offset:9216
	v_add_u32_e32 v2, s27, v208
	s_add_i32 s27, s26, 1
	s_cmp_lg_u32 s26, 4
	s_cselect_b32 s26, s27, 0
	s_add_i32 s27, s13, -5
	s_min_u32 s27, s27, s12
	s_lshl_b32 s92, s27, 13
	s_waitcnt vmcnt(2)
	ds_write_b128 v2, v[6:9] offset:36864
	s_add_u32 vcc_lo, s100, s92
	s_addc_u32 vcc_hi, s101, 0
	global_load_dwordx4 v[6:9], v248, vcc
	s_lshl_b32 s92, s28, 7
	s_add_u32 vcc_lo, s98, s92
	s_addc_u32 vcc_hi, s99, 0
	global_load_dwordx4 v[2:5], v249, vcc
	s_nop 0
	s_mul_i32 s28, s26, 0x2400
	s_add_i32 s29, s28, 0xffffdc00
	s_cmp_lg_u32 s26, 0
	s_cselect_b32 s29, s29, 0x9000
	v_add_u32_e32 v92, s29, v195
	ds_read_b128 v[64:67], v92 offset:36864
	ds_read_b128 v[68:71], v92 offset:36896
	ds_read_b128 v[72:75], v92 offset:41472
	ds_read_b128 v[76:79], v92 offset:41504
	ds_read_b128 v[80:83], v92 offset:36928
	ds_read_b128 v[84:87], v92 offset:36960
	ds_read_b128 v[88:91], v92 offset:41536
	ds_read_b128 v[92:95], v92 offset:41568
	s_setprio 3
	v_cvt_pk_bf16_f32 v112, v166, v167
	v_cvt_pk_bf16_f32 v113, v185, v186
	v_cvt_pk_bf16_f32 v114, v128, v129
	v_cvt_pk_bf16_f32 v115, v130, v131
	s_waitcnt lgkmcnt(7)
	s_nop 0
	v_mfma_f32_32x32x16_bf16 v[16:31], v[64:67], v[112:115], v[16:31]
	v_add_f32_e32 v213, v166, v167
	v_add_f32_e32 v213, v213, v185
	v_add_f32_e32 v213, v213, v186
	s_waitcnt lgkmcnt(5)
	v_mfma_f32_32x32x16_bf16 v[32:47], v[72:75], v[112:115], v[32:47]
	v_cvt_pk_bf16_f32 v64, v132, v133
	v_cvt_pk_bf16_f32 v65, v134, v135
	v_cvt_pk_bf16_f32 v66, v136, v137
	v_cvt_pk_bf16_f32 v67, v138, v139
	v_add_f32_e32 v213, v213, v128
	v_add_f32_e32 v213, v213, v129
	v_add_f32_e32 v213, v213, v130
	v_add_f32_e32 v213, v213, v131
	s_nop 0
	v_mfma_f32_32x32x16_bf16 v[16:31], v[68:71], v[64:67], v[16:31]
	v_add_f32_e32 v213, v213, v132
	v_add_f32_e32 v213, v213, v133
	v_add_f32_e32 v213, v213, v134
	v_add_f32_e32 v213, v213, v135
	s_waitcnt lgkmcnt(4)
	v_mfma_f32_32x32x16_bf16 v[32:47], v[76:79], v[64:67], v[32:47]
	v_cvt_pk_bf16_f32 v68, v140, v141
	v_cvt_pk_bf16_f32 v69, v142, v143
	v_cvt_pk_bf16_f32 v70, v187, v210
	v_cvt_pk_bf16_f32 v71, v211, v212
	v_add_f32_e32 v213, v213, v136
	v_add_f32_e32 v213, v213, v137
	v_add_f32_e32 v213, v213, v138
	v_add_f32_e32 v213, v213, v139
	s_waitcnt lgkmcnt(3)
	v_mfma_f32_32x32x16_bf16 v[16:31], v[80:83], v[68:71], v[16:31]
	v_add_f32_e32 v213, v213, v140
	v_add_f32_e32 v213, v213, v141
	v_add_f32_e32 v213, v213, v142
	v_add_f32_e32 v213, v213, v143
	s_waitcnt lgkmcnt(1)
	v_mfma_f32_32x32x16_bf16 v[32:47], v[88:91], v[68:71], v[32:47]
	v_cvt_pk_bf16_f32 v64, v116, v117
	v_cvt_pk_bf16_f32 v65, v118, v119
	v_cvt_pk_bf16_f32 v66, v120, v121
	v_cvt_pk_bf16_f32 v67, v122, v123
	v_add_f32_e32 v213, v213, v187
	v_add_f32_e32 v213, v213, v210
	v_add_f32_e32 v213, v213, v211
	v_add_f32_e32 v213, v213, v212
	s_nop 0
	v_mfma_f32_32x32x16_bf16 v[16:31], v[84:87], v[64:67], v[16:31]
	v_add_f32_e32 v213, v213, v116
	v_add_f32_e32 v213, v213, v117
	v_add_f32_e32 v213, v213, v118
	v_add_f32_e32 v213, v213, v119
	s_waitcnt lgkmcnt(0)
	v_mfma_f32_32x32x16_bf16 v[32:47], v[92:95], v[64:67], v[32:47]
	v_add_f32_e32 v213, v213, v120
	v_add_f32_e32 v213, v213, v121
	v_add_f32_e32 v213, v213, v122
	v_add_f32_e32 v213, v213, v123
	s_setprio 2
	s_waitcnt lgkmcnt(0)
	s_barrier
	ds_read_b128 v[240:243], v195
	ds_read_b128 v[244:247], v195 offset:4608
	ds_read_b128 v[116:119], v195 offset:32
	ds_read_b128 v[120:123], v195 offset:4640
	ds_read_b128 v[124:127], v195 offset:64
	ds_read_b128 v[128:131], v195 offset:4672
	ds_read_b128 v[132:135], v195 offset:96
	ds_read_b128 v[136:139], v195 offset:4704
	v_add_f32_e32 v1, v1, v184
	s_waitcnt lgkmcnt(6)
	v_mfma_f32_32x32x16_bf16 v[80:95], v[240:243], v[180:183], v[48:63]
	v_exp_f32_e32 v140, v144
	v_exp_f32_e32 v141, v145
	v_exp_f32_e32 v142, v146
	v_exp_f32_e32 v143, v147
	v_mfma_f32_32x32x16_bf16 v[64:79], v[244:247], v[180:183], v[48:63]
	v_exp_f32_e32 v144, v148
	v_exp_f32_e32 v145, v149
	v_exp_f32_e32 v146, v150
	v_exp_f32_e32 v147, v151
	s_waitcnt lgkmcnt(5)
	v_mfma_f32_32x32x16_bf16 v[80:95], v[116:119], v[176:179], v[80:95]
	v_exp_f32_e32 v148, v152
	v_exp_f32_e32 v149, v153
	v_exp_f32_e32 v150, v154
	v_exp_f32_e32 v151, v155
	s_waitcnt lgkmcnt(4)
	v_mfma_f32_32x32x16_bf16 v[64:79], v[120:123], v[176:179], v[64:79]
	v_exp_f32_e32 v152, v156
	v_exp_f32_e32 v153, v157
	v_exp_f32_e32 v154, v158
	v_exp_f32_e32 v155, v159
	s_waitcnt lgkmcnt(3)
	v_mfma_f32_32x32x16_bf16 v[80:95], v[124:127], v[172:175], v[80:95]
	v_exp_f32_e32 v156, v96
	v_exp_f32_e32 v157, v97
	v_exp_f32_e32 v158, v98
	v_exp_f32_e32 v159, v99
	s_waitcnt lgkmcnt(2)
	v_mfma_f32_32x32x16_bf16 v[64:79], v[128:131], v[172:175], v[64:79]
	v_exp_f32_e32 v166, v100
	v_exp_f32_e32 v167, v101
	v_exp_f32_e32 v184, v102
	v_exp_f32_e32 v185, v103
	s_waitcnt lgkmcnt(1)
	v_mfma_f32_32x32x16_bf16 v[80:95], v[132:135], v[168:171], v[80:95]
	v_exp_f32_e32 v186, v104
	v_exp_f32_e32 v187, v105
	v_exp_f32_e32 v210, v106
	v_exp_f32_e32 v211, v107
	s_waitcnt lgkmcnt(0)
	v_mfma_f32_32x32x16_bf16 v[64:79], v[136:139], v[168:171], v[64:79]
	v_exp_f32_e32 v212, v108
	v_exp_f32_e32 v214, v109
	v_exp_f32_e32 v215, v110
	v_exp_f32_e32 v216, v111
	v_add_u32_e32 v124, s28, v195
	ds_read_b128 v[240:243], v195 offset:9216
	ds_read_b128 v[244:247], v195 offset:13824
	ds_read_b128 v[96:99], v124 offset:41472
	ds_read_b128 v[100:103], v124 offset:36864
	ds_read_b128 v[104:107], v124 offset:36896
	ds_read_b128 v[108:111], v124 offset:41504
	ds_read_b128 v[112:115], v124 offset:36928
	ds_read_b128 v[116:119], v124 offset:41536
	ds_read_b128 v[120:123], v124 offset:36960
	ds_read_b128 v[124:127], v124 offset:41568
	s_cmp_gt_i32 s26, 2
	s_cselect_b32 s29, -3, 2
	s_add_i32 s29, s29, s26
	s_mulk_i32 s29, 0x2400
	s_waitcnt vmcnt(3)
	ds_write_b128 v208, v[10:13] offset:18432
	v_add_u32_e32 v10, s29, v208
	s_mov_b32 s29, 0x1da90000
	s_waitcnt vmcnt(2)
	ds_write_b128 v10, v[160:163] offset:36864
	s_add_i32 s92, s13, -4
	s_lshl_b32 s92, s92, 13
	s_add_u32 vcc_lo, s100, s92
	s_addc_u32 vcc_hi, s101, 0
	global_load_dwordx4 v[128:131], v248, vcc
	s_lshl_b32 s92, s27, 7
	s_add_u32 vcc_lo, s98, s92
	s_addc_u32 vcc_hi, s99, 0
	global_load_dwordx4 v[10:13], v249, vcc
	v_add_f32_e32 v1, v1, v213
	s_add_i32 s28, s26, 1
	s_setprio 1
	v_cvt_pk_bf16_f32 v132, v140, v141
	v_cvt_pk_bf16_f32 v133, v142, v143
	v_cvt_pk_bf16_f32 v134, v144, v145
	v_cvt_pk_bf16_f32 v135, v146, v147
	s_waitcnt lgkmcnt(8)
	s_nop 0
	v_mfma_f32_32x32x16_bf16 v[16:31], v[100:103], v[132:135], v[16:31]
	v_add_f32_e32 v160, v140, v141
	v_add_f32_e32 v160, v160, v142
	v_add_f32_e32 v160, v160, v143
	s_nop 0
	v_mfma_f32_32x32x16_bf16 v[32:47], v[96:99], v[132:135], v[32:47]
	v_cvt_pk_bf16_f32 v100, v148, v149
	v_cvt_pk_bf16_f32 v101, v150, v151
	v_cvt_pk_bf16_f32 v102, v152, v153
	v_cvt_pk_bf16_f32 v103, v154, v155
	v_add_f32_e32 v160, v160, v144
	v_add_f32_e32 v160, v160, v145
	v_add_f32_e32 v160, v160, v146
	v_add_f32_e32 v160, v160, v147
	s_waitcnt lgkmcnt(7)
	v_mfma_f32_32x32x16_bf16 v[16:31], v[104:107], v[100:103], v[16:31]
	v_add_f32_e32 v160, v160, v148
	v_add_f32_e32 v160, v160, v149
	v_add_f32_e32 v160, v160, v150
	v_add_f32_e32 v160, v160, v151
	s_waitcnt lgkmcnt(6)
	v_mfma_f32_32x32x16_bf16 v[32:47], v[108:111], v[100:103], v[32:47]
	v_cvt_pk_bf16_f32 v96, v156, v157
	v_cvt_pk_bf16_f32 v97, v158, v159
	v_cvt_pk_bf16_f32 v98, v166, v167
	v_cvt_pk_bf16_f32 v99, v184, v185
	v_add_f32_e32 v160, v160, v152
	v_add_f32_e32 v160, v160, v153
	v_add_f32_e32 v160, v160, v154
	v_add_f32_e32 v160, v160, v155
	s_waitcnt lgkmcnt(5)
	v_mfma_f32_32x32x16_bf16 v[16:31], v[112:115], v[96:99], v[16:31]
	v_add_f32_e32 v160, v160, v156
	v_add_f32_e32 v160, v160, v157
	v_add_f32_e32 v160, v160, v158
	v_add_f32_e32 v160, v160, v159
	s_waitcnt lgkmcnt(4)
	v_mfma_f32_32x32x16_bf16 v[32:47], v[116:119], v[96:99], v[32:47]
	v_cvt_pk_bf16_f32 v100, v186, v187
	v_cvt_pk_bf16_f32 v101, v210, v211
	v_cvt_pk_bf16_f32 v102, v212, v214
	v_cvt_pk_bf16_f32 v103, v215, v216
	v_add_f32_e32 v160, v160, v166
	v_add_f32_e32 v160, v160, v167
	v_add_f32_e32 v160, v160, v184
	v_add_f32_e32 v160, v160, v185
	s_waitcnt lgkmcnt(3)
	v_mfma_f32_32x32x16_bf16 v[16:31], v[120:123], v[100:103], v[16:31]
	v_add_f32_e32 v160, v160, v186
	v_add_f32_e32 v160, v160, v187
	v_add_f32_e32 v160, v160, v210
	v_add_f32_e32 v160, v160, v211
	s_waitcnt lgkmcnt(2)
	v_mfma_f32_32x32x16_bf16 v[32:47], v[124:127], v[100:103], v[32:47]
	v_add_f32_e32 v160, v160, v212
	v_add_f32_e32 v160, v160, v214
	v_add_f32_e32 v160, v160, v215
	v_add_f32_e32 v160, v160, v216
	s_setprio 0
	ds_read_b128 v[132:135], v195 offset:9248
	ds_read_b128 v[140:143], v195 offset:13856
	ds_read_b128 v[144:147], v195 offset:9280
	ds_read_b128 v[148:151], v195 offset:9312
	ds_read_b128 v[152:155], v195 offset:13888
	ds_read_b128 v[156:159], v195 offset:13920
	s_cmp_lg_u32 s26, 4
	s_cselect_b32 s26, s28, 0
	s_waitcnt lgkmcnt(6)
	v_mfma_f32_32x32x16_bf16 v[112:127], v[240:243], v[180:183], v[48:63]
	v_exp_f32_e32 v161, v80
	v_exp_f32_e32 v162, v81
	v_exp_f32_e32 v163, v82
	v_exp_f32_e32 v164, v83
	s_waitcnt lgkmcnt(5)
	v_mfma_f32_32x32x16_bf16 v[96:111], v[244:247], v[180:183], v[48:63]
	v_exp_f32_e32 v165, v84
	v_exp_f32_e32 v166, v85
	v_exp_f32_e32 v167, v86
	v_exp_f32_e32 v184, v87
	v_mfma_f32_32x32x16_bf16 v[112:127], v[132:135], v[176:179], v[112:127]
	v_exp_f32_e32 v136, v88
	v_exp_f32_e32 v137, v89
	v_exp_f32_e32 v138, v90
	v_exp_f32_e32 v139, v91
	s_waitcnt lgkmcnt(4)
	v_mfma_f32_32x32x16_bf16 v[96:111], v[140:143], v[176:179], v[96:111]
	v_exp_f32_e32 v185, v92
	v_exp_f32_e32 v186, v93
	v_exp_f32_e32 v187, v94
	v_exp_f32_e32 v210, v95
	s_waitcnt lgkmcnt(3)
	v_mfma_f32_32x32x16_bf16 v[112:127], v[144:147], v[172:175], v[112:127]
	v_exp_f32_e32 v140, v64
	v_exp_f32_e32 v141, v65
	v_exp_f32_e32 v142, v66
	v_exp_f32_e32 v143, v67
	s_waitcnt lgkmcnt(1)
	v_mfma_f32_32x32x16_bf16 v[96:111], v[152:155], v[172:175], v[96:111]
	v_exp_f32_e32 v144, v68
	v_exp_f32_e32 v145, v69
	v_exp_f32_e32 v146, v70
	v_exp_f32_e32 v147, v71
	v_mfma_f32_32x32x16_bf16 v[112:127], v[148:151], v[168:171], v[112:127]
	v_exp_f32_e32 v152, v72
	v_exp_f32_e32 v153, v73
	v_exp_f32_e32 v154, v74
	v_exp_f32_e32 v155, v75
	s_waitcnt lgkmcnt(0)
	v_mfma_f32_32x32x16_bf16 v[96:111], v[156:159], v[168:171], v[96:111]
	v_exp_f32_e32 v148, v76
	v_exp_f32_e32 v149, v77
	v_exp_f32_e32 v150, v78
	v_exp_f32_e32 v151, v79
	s_cmp_gt_i32 s26, 2
	s_cselect_b32 s27, -3, 2
	s_add_i32 s27, s27, s26
	s_mulk_i32 s27, 0x2400
	s_waitcnt vmcnt(3)
	ds_write_b128 v208, v[6:9] offset:27648
	v_add_u32_e32 v6, s27, v208
	s_add_i32 s27, s26, 1
	s_cmp_lg_u32 s26, 4
	s_cselect_b32 s27, s27, 0
	s_add_i32 s26, s13, -3
	s_min_u32 s28, s26, s12
	s_lshl_b32 s92, s28, 13
	s_waitcnt vmcnt(2)
	ds_write_b128 v6, v[2:5] offset:36864
	s_add_u32 vcc_lo, s100, s92
	s_addc_u32 vcc_hi, s101, 0
	global_load_dwordx4 v[6:9], v248, vcc
	s_nop 0
	s_add_i32 s92, s13, -4
	s_lshl_b32 s92, s92, 7
	s_add_u32 vcc_lo, s98, s92
	s_addc_u32 vcc_hi, s99, 0
	global_load_dwordx4 v[2:5], v249, vcc
	s_mul_i32 s29, s27, 0x2400
	s_add_i32 s34, s29, 0xffffdc00
	s_cmp_lg_u32 s27, 0
	s_cselect_b32 s34, s34, 0x9000
	v_add_u32_e32 v14, s34, v195
	ds_read_b128 v[64:67], v14 offset:36864
	ds_read_b128 v[68:71], v14 offset:36896
	ds_read_b128 v[72:75], v14 offset:41472
	ds_read_b128 v[76:79], v14 offset:41504
	ds_read_b128 v[80:83], v14 offset:36928
	ds_read_b128 v[84:87], v14 offset:36960
	ds_read_b128 v[88:91], v14 offset:41536
	ds_read_b128 v[92:95], v14 offset:41568
	s_setprio 3
	v_cvt_pk_bf16_f32 v132, v161, v162
	v_cvt_pk_bf16_f32 v133, v163, v164
	v_cvt_pk_bf16_f32 v134, v165, v166
	v_cvt_pk_bf16_f32 v135, v167, v184
	s_waitcnt lgkmcnt(7)
	s_nop 0
	v_mfma_f32_32x32x16_bf16 v[16:31], v[64:67], v[132:135], v[16:31]
	v_add_f32_e32 v14, v161, v162
	v_add_f32_e32 v14, v14, v163
	v_add_f32_e32 v14, v14, v164
	s_waitcnt lgkmcnt(5)
	v_mfma_f32_32x32x16_bf16 v[32:47], v[72:75], v[132:135], v[32:47]
	v_cvt_pk_bf16_f32 v64, v136, v137
	v_cvt_pk_bf16_f32 v65, v138, v139
	v_cvt_pk_bf16_f32 v66, v185, v186
	v_cvt_pk_bf16_f32 v67, v187, v210
	v_add_f32_e32 v14, v14, v165
	v_add_f32_e32 v14, v14, v166
	v_add_f32_e32 v14, v14, v167
	v_add_f32_e32 v14, v14, v184
	s_nop 0
	v_mfma_f32_32x32x16_bf16 v[16:31], v[68:71], v[64:67], v[16:31]
	v_add_f32_e32 v14, v14, v136
	v_add_f32_e32 v14, v14, v137
	v_add_f32_e32 v14, v14, v138
	v_add_f32_e32 v14, v14, v139
	s_waitcnt lgkmcnt(4)
	v_mfma_f32_32x32x16_bf16 v[32:47], v[76:79], v[64:67], v[32:47]
	v_cvt_pk_bf16_f32 v68, v140, v141
	v_cvt_pk_bf16_f32 v69, v142, v143
	v_cvt_pk_bf16_f32 v70, v144, v145
	v_cvt_pk_bf16_f32 v71, v146, v147
	v_add_f32_e32 v14, v14, v185
	v_add_f32_e32 v14, v14, v186
	v_add_f32_e32 v14, v14, v187
	v_add_f32_e32 v14, v14, v210
	s_waitcnt lgkmcnt(3)
	v_mfma_f32_32x32x16_bf16 v[16:31], v[80:83], v[68:71], v[16:31]
	v_add_f32_e32 v14, v14, v140
	v_add_f32_e32 v14, v14, v141
	v_add_f32_e32 v14, v14, v142
	v_add_f32_e32 v14, v14, v143
	s_waitcnt lgkmcnt(1)
	v_mfma_f32_32x32x16_bf16 v[32:47], v[88:91], v[68:71], v[32:47]
	v_cvt_pk_bf16_f32 v64, v152, v153
	v_cvt_pk_bf16_f32 v65, v154, v155
	v_cvt_pk_bf16_f32 v66, v148, v149
	v_cvt_pk_bf16_f32 v67, v150, v151
	v_add_f32_e32 v14, v14, v144
	v_add_f32_e32 v14, v14, v145
	v_add_f32_e32 v14, v14, v146
	v_add_f32_e32 v14, v14, v147
	s_nop 0
	v_mfma_f32_32x32x16_bf16 v[16:31], v[84:87], v[64:67], v[16:31]
	v_add_f32_e32 v14, v14, v152
	v_add_f32_e32 v14, v14, v153
	v_add_f32_e32 v14, v14, v154
	v_add_f32_e32 v14, v14, v155
	s_waitcnt lgkmcnt(0)
	v_mfma_f32_32x32x16_bf16 v[32:47], v[92:95], v[64:67], v[32:47]
	v_add_f32_e32 v14, v14, v148
	v_add_f32_e32 v14, v14, v149
	v_add_f32_e32 v14, v14, v150
	v_add_f32_e32 v14, v14, v151
	s_setprio 2
	s_waitcnt lgkmcnt(0)
	s_barrier
	ds_read_b128 v[240:243], v195 offset:18432
	ds_read_b128 v[244:247], v195 offset:23040
	ds_read_b128 v[136:139], v195 offset:18464
	ds_read_b128 v[140:143], v195 offset:23072
	ds_read_b128 v[144:147], v195 offset:18496
	ds_read_b128 v[148:151], v195 offset:23104
	ds_read_b128 v[152:155], v195 offset:18528
	ds_read_b128 v[156:159], v195 offset:23136
	v_add_f32_e32 v1, v1, v160
	s_waitcnt lgkmcnt(6)
	v_mfma_f32_32x32x16_bf16 v[80:95], v[240:243], v[180:183], v[48:63]
	v_exp_f32_e32 v160, v112
	v_exp_f32_e32 v161, v113
	v_exp_f32_e32 v162, v114
	v_exp_f32_e32 v163, v115
	v_mfma_f32_32x32x16_bf16 v[64:79], v[244:247], v[180:183], v[48:63]
	v_exp_f32_e32 v164, v116
	v_exp_f32_e32 v165, v117
	v_exp_f32_e32 v166, v118
	v_exp_f32_e32 v167, v119
	s_waitcnt lgkmcnt(5)
	v_mfma_f32_32x32x16_bf16 v[80:95], v[136:139], v[176:179], v[80:95]
	v_exp_f32_e32 v184, v120
	v_exp_f32_e32 v185, v121
	v_exp_f32_e32 v186, v122
	v_exp_f32_e32 v187, v123
	s_waitcnt lgkmcnt(4)
	v_mfma_f32_32x32x16_bf16 v[64:79], v[140:143], v[176:179], v[64:79]
	v_exp_f32_e32 v136, v124
	v_exp_f32_e32 v137, v125
	v_exp_f32_e32 v138, v126
	v_exp_f32_e32 v139, v127
	s_waitcnt lgkmcnt(3)
	v_mfma_f32_32x32x16_bf16 v[80:95], v[144:147], v[172:175], v[80:95]
	v_exp_f32_e32 v140, v96
	v_exp_f32_e32 v141, v97
	v_exp_f32_e32 v142, v98
	v_exp_f32_e32 v143, v99
	s_waitcnt lgkmcnt(2)
	v_mfma_f32_32x32x16_bf16 v[64:79], v[148:151], v[172:175], v[64:79]
	v_exp_f32_e32 v144, v100
	v_exp_f32_e32 v145, v101
	v_exp_f32_e32 v146, v102
	v_exp_f32_e32 v147, v103
	s_waitcnt lgkmcnt(1)
	v_mfma_f32_32x32x16_bf16 v[80:95], v[152:155], v[168:171], v[80:95]
	v_exp_f32_e32 v148, v104
	v_exp_f32_e32 v149, v105
	v_exp_f32_e32 v150, v106
	v_exp_f32_e32 v151, v107
	s_waitcnt lgkmcnt(0)
	v_mfma_f32_32x32x16_bf16 v[64:79], v[156:159], v[168:171], v[64:79]
	v_exp_f32_e32 v152, v108
	v_exp_f32_e32 v153, v109
	v_exp_f32_e32 v154, v110
	v_exp_f32_e32 v155, v111
	s_cmp_gt_i32 s27, 2
	s_cselect_b32 s34, -3, 2
	s_waitcnt vmcnt(3)
	ds_write_b128 v208, v[128:131]
	v_add_u32_e32 v128, s29, v195
	ds_read_b128 v[240:243], v195 offset:27648
	ds_read_b128 v[244:247], v195 offset:32256
	ds_read_b128 v[96:99], v128 offset:41472
	ds_read_b128 v[100:103], v128 offset:36864
	ds_read_b128 v[104:107], v128 offset:36896
	ds_read_b128 v[108:111], v128 offset:41504
	ds_read_b128 v[116:119], v128 offset:36928
	ds_read_b128 v[120:123], v128 offset:41536
	ds_read_b128 v[124:127], v128 offset:36960
	ds_read_b128 v[128:131], v128 offset:41568
	s_add_i32 s34, s34, s27
	s_add_i32 s29, s13, -2
	s_mulk_i32 s34, 0x2400
	s_min_u32 s29, s29, s12
	v_add_u32_e32 v15, s34, v208
	s_lshl_b32 s92, s29, 13
	s_waitcnt vmcnt(2)
	ds_write_b128 v15, v[10:13] offset:36864
	s_add_u32 vcc_lo, s100, s92
	s_addc_u32 vcc_hi, s101, 0
	global_load_dwordx4 v[10:13], v248, vcc
	s_lshl_b32 s92, s28, 7
	v_add_f32_e32 v1, v1, v14
	s_add_u32 vcc_lo, s98, s92
	s_addc_u32 vcc_hi, s99, 0
	global_load_dwordx4 v[112:115], v249, vcc
	s_add_i32 s34, s27, 1
	s_setprio 1
	v_cvt_pk_bf16_f32 v132, v160, v161
	v_cvt_pk_bf16_f32 v133, v162, v163
	v_cvt_pk_bf16_f32 v134, v164, v165
	v_cvt_pk_bf16_f32 v135, v166, v167
	s_waitcnt lgkmcnt(7)
	s_nop 0
	v_mfma_f32_32x32x16_bf16 v[16:31], v[100:103], v[132:135], v[16:31]
	v_add_f32_e32 v14, v160, v161
	v_add_f32_e32 v14, v14, v162
	v_add_f32_e32 v14, v14, v163
	s_nop 0
	v_mfma_f32_32x32x16_bf16 v[32:47], v[96:99], v[132:135], v[32:47]
	v_cvt_pk_bf16_f32 v100, v184, v185
	v_cvt_pk_bf16_f32 v101, v186, v187
	v_cvt_pk_bf16_f32 v102, v136, v137
	v_cvt_pk_bf16_f32 v103, v138, v139
	v_add_f32_e32 v14, v14, v164
	v_add_f32_e32 v14, v14, v165
	v_add_f32_e32 v14, v14, v166
	v_add_f32_e32 v14, v14, v167
	s_waitcnt lgkmcnt(6)
	v_mfma_f32_32x32x16_bf16 v[16:31], v[104:107], v[100:103], v[16:31]
	v_add_f32_e32 v14, v14, v184
	v_add_f32_e32 v14, v14, v185
	v_add_f32_e32 v14, v14, v186
	v_add_f32_e32 v14, v14, v187
	s_waitcnt lgkmcnt(5)
	v_mfma_f32_32x32x16_bf16 v[32:47], v[108:111], v[100:103], v[32:47]
	v_cvt_pk_bf16_f32 v96, v140, v141
	v_cvt_pk_bf16_f32 v97, v142, v143
	v_cvt_pk_bf16_f32 v98, v144, v145
	v_cvt_pk_bf16_f32 v99, v146, v147
	v_add_f32_e32 v14, v14, v136
	v_add_f32_e32 v14, v14, v137
	v_add_f32_e32 v14, v14, v138
	v_add_f32_e32 v14, v14, v139
	s_waitcnt lgkmcnt(4)
	v_mfma_f32_32x32x16_bf16 v[16:31], v[116:119], v[96:99], v[16:31]
	v_add_f32_e32 v14, v14, v140
	v_add_f32_e32 v14, v14, v141
	v_add_f32_e32 v14, v14, v142
	v_add_f32_e32 v14, v14, v143
	s_waitcnt lgkmcnt(3)
	v_mfma_f32_32x32x16_bf16 v[32:47], v[120:123], v[96:99], v[32:47]
	v_cvt_pk_bf16_f32 v100, v148, v149
	v_cvt_pk_bf16_f32 v101, v150, v151
	v_cvt_pk_bf16_f32 v102, v152, v153
	v_cvt_pk_bf16_f32 v103, v154, v155
	v_add_f32_e32 v14, v14, v144
	v_add_f32_e32 v14, v14, v145
	v_add_f32_e32 v14, v14, v146
	v_add_f32_e32 v14, v14, v147
	s_waitcnt lgkmcnt(2)
	v_mfma_f32_32x32x16_bf16 v[16:31], v[124:127], v[100:103], v[16:31]
	v_add_f32_e32 v14, v14, v148
	v_add_f32_e32 v14, v14, v149
	v_add_f32_e32 v14, v14, v150
	v_add_f32_e32 v14, v14, v151
	s_waitcnt lgkmcnt(1)
	v_mfma_f32_32x32x16_bf16 v[32:47], v[128:131], v[100:103], v[32:47]
	v_add_f32_e32 v14, v14, v152
	v_add_f32_e32 v14, v14, v153
	v_add_f32_e32 v14, v14, v154
	v_add_f32_e32 v14, v14, v155
	s_setprio 0
	ds_read_b128 v[116:119], v195 offset:27680
	ds_read_b128 v[124:127], v195 offset:32288
	ds_read_b128 v[128:131], v195 offset:27712
	ds_read_b128 v[132:135], v195 offset:27744
	ds_read_b128 v[136:139], v195 offset:32320
	ds_read_b128 v[140:143], v195 offset:32352
	s_cmp_lg_u32 s27, 4
	s_cselect_b32 s27, s34, 0
	s_waitcnt lgkmcnt(6)
	v_mfma_f32_32x32x16_bf16 v[152:167], v[240:243], v[180:183], v[48:63]
	v_exp_f32_e32 v15, v80
	v_exp_f32_e32 v144, v81
	v_exp_f32_e32 v145, v82
	v_exp_f32_e32 v146, v83
	s_waitcnt lgkmcnt(5)
	v_mfma_f32_32x32x16_bf16 v[96:111], v[244:247], v[180:183], v[48:63]
	v_exp_f32_e32 v147, v84
	v_exp_f32_e32 v148, v85
	v_exp_f32_e32 v149, v86
	v_exp_f32_e32 v150, v87
	v_mfma_f32_32x32x16_bf16 v[152:167], v[116:119], v[176:179], v[152:167]
	v_exp_f32_e32 v120, v88
	v_exp_f32_e32 v121, v89
	v_exp_f32_e32 v122, v90
	v_exp_f32_e32 v123, v91
	s_waitcnt lgkmcnt(4)
	v_mfma_f32_32x32x16_bf16 v[96:111], v[124:127], v[176:179], v[96:111]
	v_exp_f32_e32 v151, v92
	v_exp_f32_e32 v184, v93
	v_exp_f32_e32 v185, v94
	v_exp_f32_e32 v186, v95
	s_waitcnt lgkmcnt(3)
	v_mfma_f32_32x32x16_bf16 v[152:167], v[128:131], v[172:175], v[152:167]
	v_exp_f32_e32 v124, v64
	v_exp_f32_e32 v125, v65
	v_exp_f32_e32 v126, v66
	v_exp_f32_e32 v127, v67
	s_waitcnt lgkmcnt(1)
	v_mfma_f32_32x32x16_bf16 v[96:111], v[136:139], v[172:175], v[96:111]
	v_exp_f32_e32 v128, v68
	v_exp_f32_e32 v129, v69
	v_exp_f32_e32 v130, v70
	v_exp_f32_e32 v131, v71
	v_mfma_f32_32x32x16_bf16 v[152:167], v[132:135], v[168:171], v[152:167]
	v_exp_f32_e32 v136, v72
	v_exp_f32_e32 v137, v73
	v_exp_f32_e32 v138, v74
	v_exp_f32_e32 v139, v75
	s_waitcnt lgkmcnt(0)
	v_mfma_f32_32x32x16_bf16 v[96:111], v[140:143], v[168:171], v[96:111]
	v_exp_f32_e32 v132, v76
	v_exp_f32_e32 v133, v77
	v_exp_f32_e32 v134, v78
	v_exp_f32_e32 v135, v79
	s_cmp_gt_i32 s27, 2
	s_cselect_b32 s28, -3, 2
	s_add_i32 s28, s28, s27
	s_mulk_i32 s28, 0x2400
	s_waitcnt vmcnt(3)
	ds_write_b128 v208, v[6:9] offset:9216
	v_add_u32_e32 v6, s28, v208
	s_add_i32 s28, s27, 1
	s_cmp_lg_u32 s27, 4
	s_cselect_b32 s27, s28, 0
	s_add_i32 s28, s13, -1
	s_min_u32 s28, s28, s12
	s_lshl_b32 s92, s28, 13
	s_waitcnt vmcnt(2)
	ds_write_b128 v6, v[2:5] offset:36864
	s_add_u32 vcc_lo, s100, s92
	s_addc_u32 vcc_hi, s101, 0
	global_load_dwordx4 v[6:9], v248, vcc
	s_lshl_b32 s92, s29, 7
	s_add_u32 vcc_lo, s98, s92
	s_addc_u32 vcc_hi, s99, 0
	global_load_dwordx4 v[2:5], v249, vcc
	s_nop 0
	s_mul_i32 s29, s27, 0x2400
	s_add_i32 s34, s29, 0xffffdc00
	s_cmp_lg_u32 s27, 0
	s_cselect_b32 s34, s34, 0x9000
	v_add_u32_e32 v92, s34, v195
	ds_read_b128 v[64:67], v92 offset:36864
	ds_read_b128 v[68:71], v92 offset:36896
	ds_read_b128 v[72:75], v92 offset:41472
	ds_read_b128 v[76:79], v92 offset:41504
	ds_read_b128 v[80:83], v92 offset:36928
	ds_read_b128 v[84:87], v92 offset:36960
	ds_read_b128 v[88:91], v92 offset:41536
	ds_read_b128 v[92:95], v92 offset:41568
	s_setprio 3
	v_cvt_pk_bf16_f32 v116, v15, v144
	v_cvt_pk_bf16_f32 v117, v145, v146
	v_cvt_pk_bf16_f32 v118, v147, v148
	v_cvt_pk_bf16_f32 v119, v149, v150
	s_waitcnt lgkmcnt(7)
	s_nop 0
	v_mfma_f32_32x32x16_bf16 v[16:31], v[64:67], v[116:119], v[16:31]
	v_add_f32_e32 v187, v15, v144
	v_add_f32_e32 v187, v187, v145
	v_add_f32_e32 v187, v187, v146
	s_waitcnt lgkmcnt(5)
	v_mfma_f32_32x32x16_bf16 v[32:47], v[72:75], v[116:119], v[32:47]
	v_cvt_pk_bf16_f32 v64, v120, v121
	v_cvt_pk_bf16_f32 v65, v122, v123
	v_cvt_pk_bf16_f32 v66, v151, v184
	v_cvt_pk_bf16_f32 v67, v185, v186
	v_add_f32_e32 v187, v187, v147
	v_add_f32_e32 v187, v187, v148
	v_add_f32_e32 v187, v187, v149
	v_add_f32_e32 v187, v187, v150
	s_nop 0
	v_mfma_f32_32x32x16_bf16 v[16:31], v[68:71], v[64:67], v[16:31]
	v_add_f32_e32 v187, v187, v120
	v_add_f32_e32 v187, v187, v121
	v_add_f32_e32 v187, v187, v122
	v_add_f32_e32 v187, v187, v123
	s_waitcnt lgkmcnt(4)
	v_mfma_f32_32x32x16_bf16 v[32:47], v[76:79], v[64:67], v[32:47]
	v_cvt_pk_bf16_f32 v68, v124, v125
	v_cvt_pk_bf16_f32 v69, v126, v127
	v_cvt_pk_bf16_f32 v70, v128, v129
	v_cvt_pk_bf16_f32 v71, v130, v131
	v_add_f32_e32 v187, v187, v151
	v_add_f32_e32 v187, v187, v184
	v_add_f32_e32 v187, v187, v185
	v_add_f32_e32 v187, v187, v186
	s_waitcnt lgkmcnt(3)
	v_mfma_f32_32x32x16_bf16 v[16:31], v[80:83], v[68:71], v[16:31]
	v_add_f32_e32 v187, v187, v124
	v_add_f32_e32 v187, v187, v125
	v_add_f32_e32 v187, v187, v126
	v_add_f32_e32 v187, v187, v127
	s_waitcnt lgkmcnt(1)
	v_mfma_f32_32x32x16_bf16 v[32:47], v[88:91], v[68:71], v[32:47]
	v_cvt_pk_bf16_f32 v64, v136, v137
	v_cvt_pk_bf16_f32 v65, v138, v139
	v_cvt_pk_bf16_f32 v66, v132, v133
	v_cvt_pk_bf16_f32 v67, v134, v135
	v_add_f32_e32 v187, v187, v128
	v_add_f32_e32 v187, v187, v129
	v_add_f32_e32 v187, v187, v130
	v_add_f32_e32 v187, v187, v131
	s_nop 0
	v_mfma_f32_32x32x16_bf16 v[16:31], v[84:87], v[64:67], v[16:31]
	v_add_f32_e32 v187, v187, v136
	v_add_f32_e32 v187, v187, v137
	v_add_f32_e32 v187, v187, v138
	v_add_f32_e32 v187, v187, v139
	s_waitcnt lgkmcnt(0)
	v_mfma_f32_32x32x16_bf16 v[32:47], v[92:95], v[64:67], v[32:47]
	v_add_f32_e32 v187, v187, v132
	v_add_f32_e32 v187, v187, v133
	v_add_f32_e32 v187, v187, v134
	v_add_f32_e32 v187, v187, v135
	s_setprio 2
	s_waitcnt lgkmcnt(0)
	s_barrier
	ds_read_b128 v[240:243], v195
	ds_read_b128 v[244:247], v195 offset:4608
	ds_read_b128 v[72:75], v195 offset:32
	ds_read_b128 v[76:79], v195 offset:4640
	ds_read_b128 v[80:83], v195 offset:64
	ds_read_b128 v[84:87], v195 offset:4672
	ds_read_b128 v[88:91], v195 offset:96
	ds_read_b128 v[92:95], v195 offset:4704
	v_add_f32_e32 v1, v1, v14
	s_waitcnt lgkmcnt(6)
	v_mfma_f32_32x32x16_bf16 v[136:151], v[240:243], v[180:183], v[48:63]
	v_exp_f32_e32 v14, v152
	v_exp_f32_e32 v15, v153
	v_exp_f32_e32 v116, v154
	v_exp_f32_e32 v117, v155
	v_mfma_f32_32x32x16_bf16 v[120:135], v[244:247], v[180:183], v[48:63]
	v_exp_f32_e32 v118, v156
	v_exp_f32_e32 v119, v157
	v_exp_f32_e32 v184, v158
	v_exp_f32_e32 v185, v159
	s_waitcnt lgkmcnt(5)
	v_mfma_f32_32x32x16_bf16 v[136:151], v[72:75], v[176:179], v[136:151]
	v_exp_f32_e32 v186, v160
	v_exp_f32_e32 v210, v161
	v_exp_f32_e32 v211, v162
	v_exp_f32_e32 v212, v163
	s_waitcnt lgkmcnt(4)
	v_mfma_f32_32x32x16_bf16 v[120:135], v[76:79], v[176:179], v[120:135]
	v_exp_f32_e32 v160, v164
	v_exp_f32_e32 v161, v165
	v_exp_f32_e32 v162, v166
	v_exp_f32_e32 v163, v167
	s_waitcnt lgkmcnt(3)
	v_mfma_f32_32x32x16_bf16 v[136:151], v[80:83], v[172:175], v[136:151]
	v_exp_f32_e32 v164, v96
	v_exp_f32_e32 v165, v97
	v_exp_f32_e32 v166, v98
	v_exp_f32_e32 v167, v99
	s_waitcnt lgkmcnt(2)
	v_mfma_f32_32x32x16_bf16 v[120:135], v[84:87], v[172:175], v[120:135]
	v_exp_f32_e32 v96, v100
	v_exp_f32_e32 v97, v101
	v_exp_f32_e32 v98, v102
	v_exp_f32_e32 v99, v103
	s_waitcnt lgkmcnt(1)
	v_mfma_f32_32x32x16_bf16 v[136:151], v[88:91], v[168:171], v[136:151]
	v_exp_f32_e32 v100, v104
	v_exp_f32_e32 v101, v105
	v_exp_f32_e32 v102, v106
	v_exp_f32_e32 v103, v107
	s_waitcnt lgkmcnt(0)
	v_mfma_f32_32x32x16_bf16 v[120:135], v[92:95], v[168:171], v[120:135]
	v_exp_f32_e32 v104, v108
	v_exp_f32_e32 v105, v109
	v_exp_f32_e32 v106, v110
	v_exp_f32_e32 v107, v111
	s_cmp_gt_i32 s27, 2
	s_cselect_b32 s34, -3, 2
	s_add_i32 s34, s34, s27
	s_mulk_i32 s34, 0x2400
	v_add_u32_e32 v88, s29, v195
	s_min_u32 s29, s13, s12
	s_waitcnt vmcnt(3)
	ds_write_b128 v208, v[10:13] offset:18432
	v_add_u32_e32 v10, s34, v208
	s_lshl_b32 s92, s29, 13
	s_waitcnt vmcnt(2)
	ds_write_b128 v10, v[112:115] offset:36864
	ds_read_b128 v[240:243], v195 offset:9216
	ds_read_b128 v[244:247], v195 offset:13824
	ds_read_b128 v[10:13], v88 offset:41472
	ds_read_b128 v[64:67], v88 offset:36864
	ds_read_b128 v[68:71], v88 offset:36896
	ds_read_b128 v[72:75], v88 offset:41504
	ds_read_b128 v[76:79], v88 offset:36928
	ds_read_b128 v[80:83], v88 offset:41536
	ds_read_b128 v[84:87], v88 offset:36960
	ds_read_b128 v[88:91], v88 offset:41568
	s_add_u32 vcc_lo, s100, s92
	s_addc_u32 vcc_hi, s101, 0
	global_load_dwordx4 v[152:155], v248, vcc
	s_lshl_b32 s92, s28, 7
	s_add_u32 vcc_lo, s98, s92
	s_addc_u32 vcc_hi, s99, 0
	global_load_dwordx4 v[156:159], v249, vcc
	v_add_f32_e32 v1, v1, v187
	s_setprio 1
	v_mov_b32_e32 v109, v136
	v_cvt_pk_bf16_f32 v92, v14, v15
	v_cvt_pk_bf16_f32 v93, v116, v117
	v_cvt_pk_bf16_f32 v94, v118, v119
	v_cvt_pk_bf16_f32 v95, v184, v185
	s_waitcnt lgkmcnt(6)
	s_nop 0
	v_mfma_f32_32x32x16_bf16 v[16:31], v[64:67], v[92:95], v[16:31]
	v_max3_f32 v109, v109, v137, v138
	v_max3_f32 v109, v109, v139, v140
	v_add_f32_e32 v108, v14, v15
	v_add_f32_e32 v108, v108, v116
	v_add_f32_e32 v108, v108, v117
	s_nop 0
	v_mfma_f32_32x32x16_bf16 v[32:47], v[10:13], v[92:95], v[32:47]
	v_cvt_pk_bf16_f32 v64, v186, v210
	v_cvt_pk_bf16_f32 v65, v211, v212
	v_cvt_pk_bf16_f32 v66, v160, v161
	v_cvt_pk_bf16_f32 v67, v162, v163
	v_max3_f32 v109, v109, v141, v142
	v_max3_f32 v109, v109, v143, v144
	v_add_f32_e32 v108, v108, v118
	v_add_f32_e32 v108, v108, v119
	v_add_f32_e32 v108, v108, v184
	v_add_f32_e32 v108, v108, v185
	s_waitcnt lgkmcnt(5)
	v_mfma_f32_32x32x16_bf16 v[16:31], v[68:71], v[64:67], v[16:31]
	v_max3_f32 v109, v109, v145, v146
	v_max3_f32 v109, v109, v147, v148
	v_add_f32_e32 v108, v108, v186
	v_add_f32_e32 v108, v108, v210
	v_add_f32_e32 v108, v108, v211
	v_add_f32_e32 v108, v108, v212
	s_waitcnt lgkmcnt(4)
	v_mfma_f32_32x32x16_bf16 v[32:47], v[72:75], v[64:67], v[32:47]
	v_cvt_pk_bf16_f32 v10, v164, v165
	v_cvt_pk_bf16_f32 v11, v166, v167
	v_cvt_pk_bf16_f32 v12, v96, v97
	v_cvt_pk_bf16_f32 v13, v98, v99
	v_max3_f32 v109, v109, v149, v150
	v_max3_f32 v109, v109, v151, v120
	v_add_f32_e32 v108, v108, v160
	v_add_f32_e32 v108, v108, v161
	v_add_f32_e32 v108, v108, v162
	v_add_f32_e32 v108, v108, v163
	s_waitcnt lgkmcnt(3)
	v_mfma_f32_32x32x16_bf16 v[16:31], v[76:79], v[10:13], v[16:31]
	v_max3_f32 v109, v109, v121, v122
	v_max3_f32 v109, v109, v123, v124
	v_add_f32_e32 v108, v108, v164
	v_add_f32_e32 v108, v108, v165
	v_add_f32_e32 v108, v108, v166
	v_add_f32_e32 v108, v108, v167
	s_waitcnt lgkmcnt(2)
	v_mfma_f32_32x32x16_bf16 v[32:47], v[80:83], v[10:13], v[32:47]
	v_cvt_pk_bf16_f32 v64, v100, v101
	v_cvt_pk_bf16_f32 v65, v102, v103
	v_cvt_pk_bf16_f32 v66, v104, v105
	v_cvt_pk_bf16_f32 v67, v106, v107
	v_max3_f32 v109, v109, v125, v126
	v_max3_f32 v109, v109, v127, v128
	v_add_f32_e32 v108, v108, v96
	v_add_f32_e32 v108, v108, v97
	v_add_f32_e32 v108, v108, v98
	v_add_f32_e32 v108, v108, v99
	s_waitcnt lgkmcnt(1)
	v_mfma_f32_32x32x16_bf16 v[16:31], v[84:87], v[64:67], v[16:31]
	v_max3_f32 v109, v109, v129, v130
	v_max3_f32 v109, v109, v131, v132
	v_add_f32_e32 v108, v108, v100
	v_add_f32_e32 v108, v108, v101
	v_add_f32_e32 v108, v108, v102
	v_add_f32_e32 v108, v108, v103
	s_waitcnt lgkmcnt(0)
	v_mfma_f32_32x32x16_bf16 v[32:47], v[88:91], v[64:67], v[32:47]
	v_max3_f32 v109, v109, v133, v134
	v_max3_f32 v109, v109, v135, v135
	v_add_f32_e32 v108, v108, v104
	v_add_f32_e32 v108, v108, v105
	v_add_f32_e32 v108, v108, v106
	v_add_f32_e32 v108, v108, v107
	s_setprio 0
	ds_read_b128 v[164:167], v195 offset:9248
	ds_read_b128 v[160:163], v195 offset:13856
	ds_read_b128 v[74:77], v195 offset:9280
	ds_read_b128 v[66:69], v195 offset:9312
	ds_read_b128 v[70:73], v195 offset:13888
	ds_read_b128 v[10:13], v195 offset:13920
	v_add_f32_e32 v64, v1, v108
	v_mov_b32_e32 v1, v109
	s_nop 1
	v_permlane32_swap_b32_e32 v109, v1
	v_max_f32_e32 v1, v1, v1
	v_max_f32_e32 v14, v109, v109
	v_max_f32_e32 v1, v14, v1
	v_cmp_lt_f32_e32 vcc, s52, v1
	s_cbranch_vccz .LBB0_663
	v_max_f32_e32 v1, v1, v1
	v_max_f32_e32 v14, 0, v1
	v_add_f32_e32 v209, v209, v14
	v_xor_b32_e32 v48, 0x80000000, v209
	v_pk_add_f32 v[136:137], v[136:137], v[14:15] op_sel_hi:[1,0] neg_lo:[0,1] neg_hi:[0,1]
	v_pk_add_f32 v[120:121], v[120:121], v[14:15] op_sel_hi:[1,0] neg_lo:[0,1] neg_hi:[0,1]
	v_pk_add_f32 v[138:139], v[138:139], v[14:15] op_sel_hi:[1,0] neg_lo:[0,1] neg_hi:[0,1]
	v_pk_add_f32 v[122:123], v[122:123], v[14:15] op_sel_hi:[1,0] neg_lo:[0,1] neg_hi:[0,1]
	v_pk_add_f32 v[140:141], v[140:141], v[14:15] op_sel_hi:[1,0] neg_lo:[0,1] neg_hi:[0,1]
	v_pk_add_f32 v[124:125], v[124:125], v[14:15] op_sel_hi:[1,0] neg_lo:[0,1] neg_hi:[0,1]
	v_pk_add_f32 v[142:143], v[142:143], v[14:15] op_sel_hi:[1,0] neg_lo:[0,1] neg_hi:[0,1]
	v_pk_add_f32 v[126:127], v[126:127], v[14:15] op_sel_hi:[1,0] neg_lo:[0,1] neg_hi:[0,1]
	v_pk_add_f32 v[144:145], v[144:145], v[14:15] op_sel_hi:[1,0] neg_lo:[0,1] neg_hi:[0,1]
	v_pk_add_f32 v[128:129], v[128:129], v[14:15] op_sel_hi:[1,0] neg_lo:[0,1] neg_hi:[0,1]
	v_pk_add_f32 v[146:147], v[146:147], v[14:15] op_sel_hi:[1,0] neg_lo:[0,1] neg_hi:[0,1]
	v_pk_add_f32 v[130:131], v[130:131], v[14:15] op_sel_hi:[1,0] neg_lo:[0,1] neg_hi:[0,1]
	v_pk_add_f32 v[148:149], v[148:149], v[14:15] op_sel_hi:[1,0] neg_lo:[0,1] neg_hi:[0,1]
	v_pk_add_f32 v[132:133], v[132:133], v[14:15] op_sel_hi:[1,0] neg_lo:[0,1] neg_hi:[0,1]
	v_pk_add_f32 v[150:151], v[150:151], v[14:15] op_sel_hi:[1,0] neg_lo:[0,1] neg_hi:[0,1]
	v_pk_add_f32 v[134:135], v[134:135], v[14:15] op_sel_hi:[1,0] neg_lo:[0,1] neg_hi:[0,1]
	v_exp_f32_e64 v14, -v14
	v_mov_b32_e32 v49, v48
	v_mov_b32_e32 v50, v48
	v_mov_b32_e32 v51, v48
	v_mov_b32_e32 v52, v48
	v_mov_b32_e32 v53, v48
	v_mov_b32_e32 v54, v48
	v_mov_b32_e32 v55, v48
	v_mov_b32_e32 v56, v48
	v_mov_b32_e32 v57, v48
	v_mov_b32_e32 v58, v48
	v_mov_b32_e32 v59, v48
	v_mov_b32_e32 v60, v48
	v_mov_b32_e32 v61, v48
	v_mov_b32_e32 v62, v48
	v_mov_b32_e32 v63, v48
	s_nop 11
	v_pk_mul_f32 v[30:31], v[30:31], v[14:15] op_sel_hi:[1,0]
	v_pk_mul_f32 v[28:29], v[28:29], v[14:15] op_sel_hi:[1,0]
	v_pk_mul_f32 v[26:27], v[26:27], v[14:15] op_sel_hi:[1,0]
	v_pk_mul_f32 v[24:25], v[24:25], v[14:15] op_sel_hi:[1,0]
	v_pk_mul_f32 v[22:23], v[22:23], v[14:15] op_sel_hi:[1,0]
	v_pk_mul_f32 v[20:21], v[20:21], v[14:15] op_sel_hi:[1,0]
	v_pk_mul_f32 v[18:19], v[18:19], v[14:15] op_sel_hi:[1,0]
	v_pk_mul_f32 v[16:17], v[16:17], v[14:15] op_sel_hi:[1,0]
	v_pk_mul_f32 v[46:47], v[46:47], v[14:15] op_sel_hi:[1,0]
	v_pk_mul_f32 v[44:45], v[44:45], v[14:15] op_sel_hi:[1,0]
	v_pk_mul_f32 v[42:43], v[42:43], v[14:15] op_sel_hi:[1,0]
	v_pk_mul_f32 v[40:41], v[40:41], v[14:15] op_sel_hi:[1,0]
	v_pk_mul_f32 v[38:39], v[38:39], v[14:15] op_sel_hi:[1,0]
	v_pk_mul_f32 v[36:37], v[36:37], v[14:15] op_sel_hi:[1,0]
	v_pk_mul_f32 v[34:35], v[34:35], v[14:15] op_sel_hi:[1,0]
	v_pk_mul_f32 v[32:33], v[32:33], v[14:15] op_sel_hi:[1,0]
	v_mul_f32_e32 v64, v64, v14
